# nt hint on the rwprep-phase plane stores (streamed out, re-read only much later), on top of v141 (nt prep loads + weight gathers)
# speedup vs baseline: 1.0085x; 1.0016x over previous
.LBB0_162:
	s_or_b64 exec, exec, s[10:11]
	v_lshlrev_b32_e32 v55, 16, v36
	v_add_f32_e32 v55, v8, v55
	v_mul_f32_e32 v55, 0xbfb8aa3b, v55
	v_exp_f32_e32 v55, v55
	s_waitcnt vmcnt(0)
	v_lshlrev_b32_e32 v122, 16, v116
	v_and_b32_e32 v123, 0xffff0000, v116
	v_pk_add_f32 v[104:105], v[104:105], v[122:123] neg_lo:[0,1] neg_hi:[0,1]
	v_add_f32_e32 v55, 1.0, v55
	v_rcp_f32_e32 v55, v55
	v_and_b32_e32 v124, 0xffff0000, v36
	v_pk_fma_f32 v[104:105], v[4:5], v[104:105], v[122:123]
	v_lshlrev_b32_e32 v125, 16, v37
	v_and_b32_e32 v126, 0xffff0000, v37
	v_mul_f32_e32 v36, 0xbf1b4598, v55
	v_mul_f32_e32 v37, 0xbfb8aa3b, v104
	v_add_f32_e32 v55, v9, v124
	v_exp_f32_e32 v37, v37
	v_mul_f32_e32 v55, 0xbfb8aa3b, v55
	v_exp_f32_e32 v55, v55
	v_lshlrev_b32_e32 v120, 16, v118
	v_and_b32_e32 v121, 0xffff0000, v118
	v_pk_add_f32 v[50:51], v[50:51], v[120:121] neg_lo:[0,1] neg_hi:[0,1]
	v_add_f32_e32 v37, 1.0, v37
	v_pk_fma_f32 v[50:51], v[0:1], v[50:51], v[120:121]
	v_rcp_f32_e32 v120, v37
	v_add_f32_e32 v37, 1.0, v55
	v_mul_f32_e32 v55, 0xbfb8aa3b, v105
	v_add_f32_e32 v121, v10, v125
	v_exp_f32_e32 v55, v55
	v_mul_f32_e32 v121, 0xbfb8aa3b, v121
	v_exp_f32_e32 v122, v121
	v_lshlrev_b32_e32 v116, 16, v117
	v_add_f32_e32 v55, 1.0, v55
	v_and_b32_e32 v117, 0xffff0000, v117
	v_rcp_f32_e32 v121, v55
	v_add_f32_e32 v55, 1.0, v122
	v_rcp_f32_e32 v55, v55
	v_pk_add_f32 v[48:49], v[48:49], v[116:117] neg_lo:[0,1] neg_hi:[0,1]
	v_rcp_f32_e32 v37, v37
	v_pk_fma_f32 v[48:49], v[6:7], v[48:49], v[116:117]
	v_add_f32_e32 v116, v11, v126
	v_mul_f32_e32 v116, 0xbfb8aa3b, v116
	v_exp_f32_e32 v116, v116
	v_mul_f32_e32 v55, 0xbf1b4598, v55
	v_mul_f32_e32 v55, 0x3fb8aa3b, v55
	v_pk_mul_f32 v[104:105], v[104:105], v[120:121]
	v_exp_f32_e32 v120, v55
	v_mul_f32_e32 v55, 0xbfb8aa3b, v48
	v_lshlrev_b32_e32 v118, 16, v119
	v_and_b32_e32 v119, 0xffff0000, v119
	v_exp_f32_e32 v55, v55
	v_add_f32_e32 v116, 1.0, v116
	v_pk_add_f32 v[40:41], v[40:41], v[118:119] neg_lo:[0,1] neg_hi:[0,1]
	v_rcp_f32_e32 v117, v116
	v_mul_f32_e32 v116, 0xbfb8aa3b, v49
	v_mul_f32_e32 v37, 0xbf1b4598, v37
	v_pk_fma_f32 v[40:41], v[2:3], v[40:41], v[118:119]
	v_exp_f32_e32 v118, v116
	v_mul_f32_e32 v36, 0x3fb8aa3b, v36
	v_mul_f32_e32 v37, 0x3fb8aa3b, v37
	v_exp_f32_e32 v36, v36
	v_exp_f32_e32 v37, v37
	v_add_f32_e32 v55, 1.0, v55
	v_add_f32_e32 v58, v58, v103
	v_rcp_f32_e32 v116, v55
	v_mul_f32_e32 v55, 0xbf1b4598, v117
	v_max_f32_e32 v58, 0x179abe15, v58
	v_mul_f32_e32 v55, 0x3fb8aa3b, v55
	v_add_f32_e32 v117, 1.0, v118
	v_rsq_f32_e32 v58, v58
	v_rcp_f32_e32 v117, v117
	v_exp_f32_e32 v121, v55
	v_pk_add_f32 v[36:37], v[36:37], -1.0 op_sel_hi:[1,0]
	v_pk_mul_f32 v[112:113], v[112:113], v[58:59] op_sel_hi:[1,0]
	v_pk_add_f32 v[36:37], v[36:37], 1.0 op_sel_hi:[1,0]
	v_pk_mul_f32 v[114:115], v[114:115], v[58:59] op_sel_hi:[1,0]
	v_mad_i64_i32 v[54:55], s[10:11], v54, s23, v[56:57]
	v_pk_mul_f32 v[36:37], v[42:43], v[36:37]
	v_pk_mul_f32 v[48:49], v[48:49], v[116:117]
	v_pk_mul_f32 v[116:117], v[42:43], v[112:113]
	v_pk_add_f32 v[118:119], v[120:121], -1.0 op_sel_hi:[1,0]
	v_pk_mul_f32 v[120:121], v[52:53], v[114:115]
	v_lshlrev_b64 v[54:55], 1, v[54:55]
	v_pk_mul_f32 v[38:39], v[38:39], v[36:37]
	v_lshl_add_u64 v[122:123], s[74:75], 0, v[54:55]
	v_lshl_add_u64 v[124:125], s[76:77], 0, v[54:55]
	v_cvt_pk_bf16_f32 v50, v50, v51
	v_cvt_pk_bf16_f32 v51, v40, v41
	v_lshl_add_u64 v[40:41], s[78:79], 0, v[54:55]
	v_cvt_pk_bf16_f32 v116, v116, v117
	v_cvt_pk_bf16_f32 v117, v120, v121
	v_lshl_add_u64 v[120:121], s[80:81], 0, v[54:55]
	v_lshl_add_u64 v[126:127], s[82:83], 0, v[54:55]
	v_cvt_pk_bf16_f32 v104, v104, v105
	v_cvt_pk_bf16_f32 v105, v48, v49
	v_lshl_add_u64 v[48:49], s[84:85], 0, v[54:55]
	v_ashrrev_i32_e32 v54, 3, v102
	v_pk_mul_f32 v[102:103], v[106:107], v[112:113]
	v_cvt_pk_bf16_f32 v106, v38, v39
	v_pk_add_f32 v[38:39], v[118:119], 1.0 op_sel_hi:[1,0]
	v_rcp_f32_e32 v42, v36
	v_pk_mul_f32 v[38:39], v[52:53], v[38:39]
	v_rcp_f32_e32 v43, v37
	v_rcp_f32_e32 v52, v38
	v_rcp_f32_e32 v53, v39
	v_ashrrev_i32_e32 v55, 31, v54
	v_pk_mul_f32 v[102:103], v[102:103], v[42:43]
	v_pk_mul_f32 v[42:43], v[108:109], v[42:43]
	v_pk_mul_f32 v[108:109], v[110:111], v[114:115]
	v_pk_mul_f32 v[44:45], v[44:45], v[38:39]
	v_pk_mul_f32 v[46:47], v[46:47], v[52:53]
	s_add_i32 s24, s24, s3
	s_add_i32 s20, s20, s21
	v_lshlrev_b64 v[54:55], 12, v[54:55]
	v_cvt_pk_bf16_f32 v42, v42, v43
	v_pk_mul_f32 v[108:109], v[108:109], v[52:53]
	v_cvt_pk_bf16_f32 v107, v44, v45
	v_cvt_pk_bf16_f32 v43, v46, v47
	s_cmpk_lt_i32 s24, 0x882
	v_lshl_add_u64 v[54:55], v[100:101], 0, v[54:55]
	v_cvt_pk_bf16_f32 v102, v102, v103
	global_store_dwordx2 v[122:123], v[106:107], off nt
	v_cvt_pk_bf16_f32 v103, v108, v109
	global_store_dwordx2 v[124:125], v[42:43], off nt
	global_store_dwordx2 v[40:41], v[50:51], off nt
	global_store_dwordx2 v[120:121], v[116:117], off nt
	global_store_dwordx2 v[126:127], v[102:103], off nt
	global_store_dwordx2 v[48:49], v[104:105], off nt
	global_store_dwordx4 v[54:55], v[36:39], off nt
	s_barrier
	s_cbranch_scc0 .LBB0_211

.LBB0_195:
	s_or_b64 exec, exec, s[16:17]
	v_add_u32_e32 v102, s20, v133
	v_mad_i64_i32 v[52:53], s[10:11], v102, s22, v[60:61]
	global_load_dwordx2 v[104:105], v[52:53], off
	global_load_dwordx2 v[120:121], v[52:53], off offset:2048
	v_add_co_u32_e32 v52, vcc, s2, v52
	s_waitcnt vmcnt(1)
	v_lshlrev_b32_e32 v118, 16, v104
	v_addc_co_u32_e32 v53, vcc, 0, v53, vcc
	global_load_dwordx2 v[108:109], v[52:53], off
	global_load_dwordx2 v[116:117], v[52:53], off offset:2048
	v_add_u32_e32 v242, 1, v102
	v_mad_i64_i32 v[242:243], s[26:27], v242, s22, v[60:61]
	global_load_dwordx2 v[246:247], v[242:243], off
	global_load_dwordx2 v[248:249], v[242:243], off offset:2048
	v_add_co_u32_e32 v244, vcc, s2, v242
	s_nop 1
	v_addc_co_u32_e32 v245, vcc, 0, v243, vcc
	global_load_dwordx2 v[250:251], v[244:245], off
	global_load_dwordx2 v[254:255], v[244:245], off offset:2048
	v_add_u32_e32 v242, 2, v102
	v_mad_i64_i32 v[242:243], s[26:27], v242, s22, v[60:61]
	global_load_dwordx2 v[234:235], v[242:243], off
	global_load_dwordx2 v[236:237], v[242:243], off offset:2048
	v_add_co_u32_e32 v244, vcc, s2, v242
	s_nop 1
	v_addc_co_u32_e32 v245, vcc, 0, v243, vcc
	global_load_dwordx2 v[238:239], v[244:245], off
	global_load_dwordx2 v[240:241], v[244:245], off offset:2048
	ds_read2st64_b64 v[52:55], v166 offset0:16 offset1:80
	v_and_b32_e32 v119, 0xffff0000, v104
	s_waitcnt vmcnt(10)
	v_lshlrev_b32_e32 v114, 16, v120
	v_and_b32_e32 v115, 0xffff0000, v120
	v_pk_add_f32 v[44:45], v[44:45], v[118:119] neg_lo:[0,1] neg_hi:[0,1]
	s_waitcnt lgkmcnt(0)
	v_lshlrev_b32_e32 v58, 16, v54
	v_and_b32_e32 v54, 0xffff0000, v54
	v_lshlrev_b32_e32 v103, 16, v55
	v_and_b32_e32 v55, 0xffff0000, v55
	v_add_f32_e32 v58, v12, v58
	v_add_f32_e32 v54, v13, v54
	v_add_f32_e32 v103, v14, v103
	v_add_f32_e32 v55, v15, v55
	v_mul_f32_e32 v58, 0xbfb8aa3b, v58
	v_mul_f32_e32 v54, 0xbfb8aa3b, v54
	v_mul_f32_e32 v103, 0xbfb8aa3b, v103
	v_mul_f32_e32 v55, 0xbfb8aa3b, v55
	v_exp_f32_e32 v58, v58
	v_exp_f32_e32 v54, v54
	v_exp_f32_e32 v103, v103
	v_exp_f32_e32 v55, v55
	v_add_f32_e32 v58, 1.0, v58
	v_add_f32_e32 v54, 1.0, v54
	v_add_f32_e32 v103, 1.0, v103
	v_add_f32_e32 v55, 1.0, v55
	v_rcp_f32_e32 v112, v58
	v_rcp_f32_e32 v113, v54
	v_rcp_f32_e32 v110, v103
	v_rcp_f32_e32 v111, v55
	v_pk_add_f32 v[48:49], v[48:49], v[114:115] neg_lo:[0,1] neg_hi:[0,1]
	v_pk_add_f32 v[54:55], v[112:113], -1.0 op_sel_hi:[1,0]
	v_pk_fma_f32 v[122:123], v[16:17], v[44:45], v[118:119]
	v_pk_add_f32 v[106:107], v[110:111], -1.0 op_sel_hi:[1,0]
	v_pk_fma_f32 v[124:125], v[28:29], v[54:55], 1.0 op_sel_hi:[1,1,0]
	v_lshlrev_b32_e32 v54, 16, v121
	v_and_b32_e32 v55, 0xffff0000, v121
	v_pk_fma_f32 v[44:45], v[20:21], v[48:49], v[114:115]
	v_pk_fma_f32 v[148:149], v[30:31], v[106:107], 1.0 op_sel_hi:[1,1,0]
	v_lshlrev_b32_e32 v106, 16, v105
	v_and_b32_e32 v107, 0xffff0000, v105
	v_pk_add_f32 v[50:51], v[50:51], v[54:55] neg_lo:[0,1] neg_hi:[0,1]
	v_pk_mul_f32 v[120:121], v[44:45], v[124:125]
	v_pk_add_f32 v[46:47], v[46:47], v[106:107] neg_lo:[0,1] neg_hi:[0,1]
	v_pk_fma_f32 v[50:51], v[22:23], v[50:51], v[54:55]
	v_pk_mul_f32 v[126:127], v[24:25], v[44:45]
	v_pk_mul_f32 v[44:45], v[122:123], v[120:121]
	v_pk_fma_f32 v[46:47], v[18:19], v[46:47], v[106:107]
	v_pk_mul_f32 v[48:49], v[50:51], v[148:149]
	v_pk_mul_f32 v[124:125], v[26:27], v[50:51]
	v_pk_mul_f32 v[50:51], v[126:127], v[126:127]
	v_fma_f32 v44, v32, v44, 0
	v_pk_mul_f32 v[104:105], v[46:47], v[48:49]
	v_pk_mul_f32 v[148:149], v[124:125], v[124:125]
	v_add_f32_e32 v50, v50, v51
	v_fmac_f32_e32 v44, v33, v45
	v_add_f32_e32 v45, v50, v148
	v_fmac_f32_e32 v44, v34, v104
	v_add_f32_e32 v45, v149, v45
	v_fmac_f32_e32 v44, v35, v105
	v_ashrrev_i32_e32 v103, 31, v102
	v_add_f32_dpp v45, v45, v45 quad_perm:[1,0,3,2] row_mask:0xf bank_mask:0xf bound_ctrl:1
	v_add_f32_dpp v44, v44, v44 quad_perm:[1,0,3,2] row_mask:0xf bank_mask:0xf bound_ctrl:1
	s_nop 0
	v_add_f32_dpp v45, v45, v45 quad_perm:[2,3,0,1] row_mask:0xf bank_mask:0xf bound_ctrl:1
	v_add_f32_dpp v44, v44, v44 quad_perm:[2,3,0,1] row_mask:0xf bank_mask:0xf bound_ctrl:1
	s_nop 0
	v_add_f32_dpp v58, v45, v45 row_half_mirror row_mask:0xf bank_mask:0xf bound_ctrl:1
	v_add_f32_dpp v44, v44, v44 row_half_mirror row_mask:0xf bank_mask:0xf bound_ctrl:1
	s_nop 0
	v_mov_b32_dpp v148, v58 row_mirror row_mask:0xf bank_mask:0xf bound_ctrl:1
	v_mov_b32_dpp v45, v44 row_mirror row_mask:0xf bank_mask:0xf bound_ctrl:1
	s_and_saveexec_b64 s[10:11], s[6:7]
	s_cbranch_execz .LBB0_197
	v_lshlrev_b64 v[50:51], 6, v[102:103]
	v_lshl_add_u64 v[50:51], v[98:99], 0, v[50:51]
	v_add_f32_e32 v44, v44, v45
	global_store_dword v[50:51], v44, off nt
.LBB0_197:
	s_or_b64 exec, exec, s[10:11]
	v_lshlrev_b32_e32 v50, 16, v52
	v_add_f32_e32 v50, v8, v50
	v_mul_f32_e32 v50, 0xbfb8aa3b, v50
	v_exp_f32_e32 v103, v50
	s_waitcnt vmcnt(8)
	v_lshlrev_b32_e32 v104, 16, v108
	v_and_b32_e32 v105, 0xffff0000, v108
	v_lshlrev_b32_e32 v44, 16, v109
	v_add_f32_e32 v103, 1.0, v103
	v_rcp_f32_e32 v103, v103
	v_and_b32_e32 v45, 0xffff0000, v109
	s_waitcnt vmcnt(8)
	v_lshlrev_b32_e32 v108, 16, v116
	v_and_b32_e32 v109, 0xffff0000, v116
	v_pk_add_f32 v[40:41], v[40:41], v[108:109] neg_lo:[0,1] neg_hi:[0,1]
	v_and_b32_e32 v116, 0xffff0000, v52
	v_pk_fma_f32 v[40:41], v[4:5], v[40:41], v[108:109]
	v_lshlrev_b32_e32 v50, 16, v117
	v_and_b32_e32 v51, 0xffff0000, v117
	v_lshlrev_b32_e32 v117, 16, v53
	v_and_b32_e32 v149, 0xffff0000, v53
	v_mul_f32_e32 v52, 0xbf1b4598, v103
	v_mul_f32_e32 v53, 0xbfb8aa3b, v40
	v_add_f32_e32 v103, v9, v116
	v_exp_f32_e32 v53, v53
	v_mul_f32_e32 v103, 0xbfb8aa3b, v103
	v_exp_f32_e32 v103, v103
	v_add_f32_e32 v117, v10, v117
	v_add_f32_e32 v53, 1.0, v53
	v_rcp_f32_e32 v116, v53
	v_add_f32_e32 v53, 1.0, v103
	v_mul_f32_e32 v103, 0xbfb8aa3b, v41
	v_exp_f32_e32 v103, v103
	v_mul_f32_e32 v117, 0xbfb8aa3b, v117
	v_exp_f32_e32 v150, v117
	v_rcp_f32_e32 v53, v53
	v_add_f32_e32 v103, 1.0, v103
	v_rcp_f32_e32 v117, v103
	v_add_f32_e32 v103, 1.0, v150
	v_rcp_f32_e32 v103, v103
	v_mul_f32_e32 v53, 0xbf1b4598, v53
	v_pk_mul_f32 v[40:41], v[40:41], v[116:117]
	v_add_f32_e32 v116, v11, v149
	v_mul_f32_e32 v116, 0xbfb8aa3b, v116
	v_exp_f32_e32 v116, v116
	v_mul_f32_e32 v52, 0x3fb8aa3b, v52
	v_mul_f32_e32 v53, 0x3fb8aa3b, v53
	v_exp_f32_e32 v52, v52
	v_add_f32_e32 v116, 1.0, v116
	v_rcp_f32_e32 v116, v116
	v_exp_f32_e32 v53, v53
	v_mul_f32_e32 v103, 0xbf1b4598, v103
	v_pk_add_f32 v[42:43], v[42:43], v[50:51] neg_lo:[0,1] neg_hi:[0,1]
	v_mul_f32_e32 v103, 0x3fb8aa3b, v103
	v_pk_fma_f32 v[42:43], v[6:7], v[42:43], v[50:51]
	v_add_f32_e32 v58, v58, v148
	v_exp_f32_e32 v150, v103
	v_mul_f32_e32 v103, 0xbfb8aa3b, v42
	v_mul_f32_e32 v116, 0xbf1b4598, v116
	v_max_f32_e32 v58, 0x179abe15, v58
	v_exp_f32_e32 v103, v103
	v_mul_f32_e32 v116, 0x3fb8aa3b, v116
	v_rsq_f32_e32 v58, v58
	v_pk_add_f32 v[52:53], v[52:53], -1.0 op_sel_hi:[1,0]
	v_exp_f32_e32 v151, v116
	v_pk_add_f32 v[116:117], v[52:53], 1.0 op_sel_hi:[1,0]
	v_add_f32_e32 v103, 1.0, v103
	v_rcp_f32_e32 v52, v116
	v_rcp_f32_e32 v53, v117
	v_pk_mul_f32 v[126:127], v[126:127], v[58:59] op_sel_hi:[1,0]
	v_rcp_f32_e32 v152, v103
	v_mul_f32_e32 v103, 0xbfb8aa3b, v43
	v_pk_mul_f32 v[112:113], v[112:113], v[126:127]
	v_exp_f32_e32 v103, v103
	v_pk_mul_f32 v[148:149], v[52:53], v[112:113]
	v_pk_add_f32 v[112:113], v[150:151], -1.0 op_sel_hi:[1,0]
	v_pk_add_f32 v[36:37], v[36:37], v[104:105] neg_lo:[0,1] neg_hi:[0,1]
	v_pk_add_f32 v[112:113], v[112:113], 1.0 op_sel_hi:[1,0]
	v_add_f32_e32 v103, 1.0, v103
	v_rcp_f32_e32 v150, v112
	v_rcp_f32_e32 v151, v113
	v_pk_add_f32 v[38:39], v[38:39], v[44:45] neg_lo:[0,1] neg_hi:[0,1]
	v_rcp_f32_e32 v153, v103
	v_pk_mul_f32 v[122:123], v[122:123], v[116:117]
	v_pk_mul_f32 v[52:53], v[52:53], v[120:121]
	v_pk_mul_f32 v[120:121], v[124:125], v[58:59] op_sel_hi:[1,0]
	v_pk_mul_f32 v[46:47], v[46:47], v[112:113]
	v_mad_i64_i32 v[124:125], s[10:11], v102, s23, v[56:57]
	v_pk_fma_f32 v[36:37], v[0:1], v[36:37], v[104:105]
	v_pk_fma_f32 v[38:39], v[2:3], v[38:39], v[44:45]
	v_pk_mul_f32 v[48:49], v[150:151], v[48:49]
	v_cvt_pk_bf16_f32 v122, v122, v123
	v_cvt_pk_bf16_f32 v123, v46, v47
	v_lshlrev_b64 v[46:47], 1, v[124:125]
	v_pk_mul_f32 v[110:111], v[110:111], v[120:121]
	v_lshl_add_u64 v[124:125], s[74:75], 0, v[46:47]
	v_cvt_pk_bf16_f32 v52, v52, v53
	v_cvt_pk_bf16_f32 v53, v48, v49
	v_lshl_add_u64 v[48:49], s[76:77], 0, v[46:47]
	v_cvt_pk_bf16_f32 v36, v36, v37
	v_cvt_pk_bf16_f32 v37, v38, v39
	v_lshl_add_u64 v[38:39], s[78:79], 0, v[46:47]
	v_pk_mul_f32 v[110:111], v[110:111], v[150:151]
	global_store_dwordx2 v[124:125], v[122:123], off nt
	global_store_dwordx2 v[48:49], v[52:53], off nt
	global_store_dwordx2 v[38:39], v[36:37], off nt
	v_cvt_pk_bf16_f32 v36, v126, v127
	v_cvt_pk_bf16_f32 v37, v120, v121
	v_lshl_add_u64 v[38:39], s[80:81], 0, v[46:47]
	v_pk_mul_f32 v[42:43], v[42:43], v[152:153]
	global_store_dwordx2 v[38:39], v[36:37], off nt
	v_cvt_pk_bf16_f32 v36, v148, v149
	v_cvt_pk_bf16_f32 v37, v110, v111
	v_lshl_add_u64 v[38:39], s[82:83], 0, v[46:47]
	global_store_dwordx2 v[38:39], v[36:37], off nt
	v_cvt_pk_bf16_f32 v36, v40, v41
	v_cvt_pk_bf16_f32 v37, v42, v43
	v_lshl_add_u64 v[38:39], s[84:85], 0, v[46:47]
	v_add_u32_e32 v120, 1, v102
	global_store_dwordx2 v[38:39], v[36:37], off nt
	v_mad_i64_i32 v[36:37], s[10:11], v120, s22, v[60:61]
	v_add_co_u32_e32 v36, vcc, s2, v36
	v_ashrrev_i32_e32 v121, 31, v120
	s_nop 0
	v_addc_co_u32_e32 v37, vcc, 0, v37, vcc
	s_waitcnt vmcnt(10)
	v_mov_b64_e32 v[40:41], v[246:247]
	v_mov_b64_e32 v[46:47], v[248:249]
	v_mov_b64_e32 v[42:43], v[250:251]
	v_mov_b64_e32 v[48:49], v[254:255]
	v_add_u32_e32 v242, 3, v102
	v_mad_i64_i32 v[242:243], s[26:27], v242, s22, v[60:61]
	global_load_dwordx2 v[246:247], v[242:243], off
	global_load_dwordx2 v[248:249], v[242:243], off offset:2048
	v_add_co_u32_e32 v244, vcc, s2, v242
	s_nop 1
	v_addc_co_u32_e32 v245, vcc, 0, v243, vcc
	global_load_dwordx2 v[250:251], v[244:245], off
	global_load_dwordx2 v[254:255], v[244:245], off offset:2048
	ds_read2st64_b64 v[36:39], v167 offset0:16 offset1:80
	s_waitcnt lgkmcnt(0)
	v_lshlrev_b32_e32 v58, 16, v38
	v_and_b32_e32 v38, 0xffff0000, v38
	v_add_f32_e32 v38, v13, v38
	v_mul_f32_e32 v38, 0xbfb8aa3b, v38
	v_lshlrev_b32_e32 v103, 16, v39
	v_and_b32_e32 v126, 0xffff0000, v39
	v_add_f32_e32 v39, v12, v58
	v_exp_f32_e32 v58, v38
	v_mul_f32_e32 v39, 0xbfb8aa3b, v39
	v_exp_f32_e32 v39, v39
	v_add_f32_e32 v58, 1.0, v58
	v_rcp_f32_e32 v123, v58
	v_add_f32_e32 v58, v14, v103
	v_mul_f32_e32 v58, 0xbfb8aa3b, v58
	v_add_f32_e32 v103, v15, v126
	v_add_f32_e32 v38, 1.0, v39
	v_exp_f32_e32 v58, v58
	v_mul_f32_e32 v103, 0xbfb8aa3b, v103
	v_rcp_f32_e32 v122, v38
	v_exp_f32_e32 v103, v103
	v_add_f32_e32 v58, 1.0, v58
	v_rcp_f32_e32 v126, v58
	v_add_f32_e32 v58, 1.0, v103
	v_rcp_f32_e32 v127, v58
	v_lshlrev_b32_e32 v52, 16, v40
	v_and_b32_e32 v53, 0xffff0000, v40
	v_lshlrev_b32_e32 v110, 16, v46
	v_and_b32_e32 v111, 0xffff0000, v46
	v_pk_add_f32 v[38:39], v[118:119], v[52:53] neg_lo:[0,1] neg_hi:[0,1]
	v_pk_add_f32 v[114:115], v[114:115], v[110:111] neg_lo:[0,1] neg_hi:[0,1]
	v_pk_add_f32 v[118:119], v[122:123], -1.0 op_sel_hi:[1,0]
	v_pk_fma_f32 v[114:115], v[20:21], v[114:115], v[110:111]
	v_pk_fma_f32 v[118:119], v[28:29], v[118:119], 1.0 op_sel_hi:[1,1,0]
	v_pk_fma_f32 v[38:39], v[16:17], v[38:39], v[52:53]
	v_pk_mul_f32 v[118:119], v[114:115], v[118:119]
	v_lshlrev_b32_e32 v40, 16, v41
	v_and_b32_e32 v41, 0xffff0000, v41
	v_lshlrev_b32_e32 v46, 16, v47
	v_and_b32_e32 v47, 0xffff0000, v47
	v_pk_mul_f32 v[124:125], v[38:39], v[118:119]
	v_pk_add_f32 v[106:107], v[106:107], v[40:41] neg_lo:[0,1] neg_hi:[0,1]
	v_fma_f32 v154, v32, v124, 0
	v_pk_add_f32 v[54:55], v[54:55], v[46:47] neg_lo:[0,1] neg_hi:[0,1]
	v_pk_mul_f32 v[148:149], v[24:25], v[114:115]
	v_fmac_f32_e32 v154, v33, v125
	v_pk_fma_f32 v[124:125], v[18:19], v[106:107], v[40:41]
	v_pk_fma_f32 v[54:55], v[22:23], v[54:55], v[46:47]
	v_pk_add_f32 v[106:107], v[126:127], -1.0 op_sel_hi:[1,0]
	v_pk_mul_f32 v[114:115], v[148:149], v[148:149]
	v_pk_fma_f32 v[106:107], v[30:31], v[106:107], 1.0 op_sel_hi:[1,1,0]
	v_pk_mul_f32 v[152:153], v[26:27], v[54:55]
	v_pk_mul_f32 v[150:151], v[54:55], v[106:107]
	v_pk_mul_f32 v[54:55], v[152:153], v[152:153]
	v_add_f32_e32 v58, v114, v115
	v_add_f32_e32 v54, v58, v54
	v_pk_mul_f32 v[106:107], v[124:125], v[150:151]
	v_add_f32_e32 v54, v55, v54
	v_fmac_f32_e32 v154, v34, v106
	v_fmac_f32_e32 v154, v35, v107
	v_add_f32_dpp v54, v54, v54 quad_perm:[1,0,3,2] row_mask:0xf bank_mask:0xf bound_ctrl:1
	s_nop 1
	v_add_f32_dpp v54, v54, v54 quad_perm:[2,3,0,1] row_mask:0xf bank_mask:0xf bound_ctrl:1
	s_nop 1
	v_add_f32_dpp v58, v54, v54 row_half_mirror row_mask:0xf bank_mask:0xf bound_ctrl:1
	v_add_f32_dpp v54, v154, v154 quad_perm:[1,0,3,2] row_mask:0xf bank_mask:0xf bound_ctrl:1
	s_nop 0
	v_mov_b32_dpp v103, v58 row_mirror row_mask:0xf bank_mask:0xf bound_ctrl:1
	v_add_f32_dpp v54, v54, v54 quad_perm:[2,3,0,1] row_mask:0xf bank_mask:0xf bound_ctrl:1
	s_nop 1
	v_add_f32_dpp v54, v54, v54 row_half_mirror row_mask:0xf bank_mask:0xf bound_ctrl:1
	s_nop 1
	v_mov_b32_dpp v55, v54 row_mirror row_mask:0xf bank_mask:0xf bound_ctrl:1
	s_and_saveexec_b64 s[10:11], s[6:7]
	s_cbranch_execz .LBB0_199
	v_lshlrev_b64 v[106:107], 6, v[120:121]
	v_lshl_add_u64 v[106:107], v[98:99], 0, v[106:107]
	v_add_f32_e32 v54, v54, v55
	global_store_dword v[106:107], v54, off nt
.LBB0_199:
	s_or_b64 exec, exec, s[10:11]
	v_lshlrev_b32_e32 v107, 16, v36
	v_add_f32_e32 v107, v8, v107
	v_mul_f32_e32 v107, 0xbfb8aa3b, v107
	v_exp_f32_e32 v114, v107
	v_lshlrev_b32_e32 v106, 16, v48
	v_and_b32_e32 v107, 0xffff0000, v48
	v_pk_add_f32 v[108:109], v[108:109], v[106:107] neg_lo:[0,1] neg_hi:[0,1]
	v_add_f32_e32 v114, 1.0, v114
	v_rcp_f32_e32 v114, v114
	v_and_b32_e32 v115, 0xffff0000, v36
	v_pk_fma_f32 v[108:109], v[4:5], v[108:109], v[106:107]
	v_lshlrev_b32_e32 v121, 16, v37
	v_and_b32_e32 v155, 0xffff0000, v37
	v_mul_f32_e32 v36, 0xbf1b4598, v114
	v_mul_f32_e32 v37, 0xbfb8aa3b, v108
	v_add_f32_e32 v114, v9, v115
	v_exp_f32_e32 v37, v37
	v_mul_f32_e32 v114, 0xbfb8aa3b, v114
	v_exp_f32_e32 v115, v114
	v_add_f32_e32 v121, v10, v121
	v_add_f32_e32 v37, 1.0, v37
	v_rcp_f32_e32 v114, v37
	v_add_f32_e32 v37, 1.0, v115
	v_mul_f32_e32 v115, 0xbfb8aa3b, v109
	v_mul_f32_e32 v121, 0xbfb8aa3b, v121
	v_exp_f32_e32 v115, v115
	v_exp_f32_e32 v121, v121
	v_lshlrev_b32_e32 v48, 16, v49
	v_and_b32_e32 v49, 0xffff0000, v49
	v_add_f32_e32 v115, 1.0, v115
	v_add_f32_e32 v121, 1.0, v121
	v_rcp_f32_e32 v115, v115
	v_rcp_f32_e32 v121, v121
	v_rcp_f32_e32 v37, v37
	v_pk_add_f32 v[50:51], v[50:51], v[48:49] neg_lo:[0,1] neg_hi:[0,1]
	v_pk_mul_f32 v[108:109], v[108:109], v[114:115]
	v_mul_f32_e32 v114, 0xbf1b4598, v121
	v_add_f32_e32 v115, v11, v155
	v_mul_f32_e32 v114, 0x3fb8aa3b, v114
	v_pk_fma_f32 v[50:51], v[6:7], v[50:51], v[48:49]
	v_mul_f32_e32 v115, 0xbfb8aa3b, v115
	v_exp_f32_e32 v154, v114
	v_mul_f32_e32 v114, 0xbfb8aa3b, v50
	v_exp_f32_e32 v115, v115
	v_mul_f32_e32 v121, 0xbfb8aa3b, v51
	v_exp_f32_e32 v114, v114
	v_exp_f32_e32 v121, v121
	v_mul_f32_e32 v37, 0xbf1b4598, v37
	v_mul_f32_e32 v36, 0x3fb8aa3b, v36
	v_mul_f32_e32 v37, 0x3fb8aa3b, v37
	v_exp_f32_e32 v36, v36
	v_exp_f32_e32 v37, v37
	v_add_f32_e32 v115, 1.0, v115
	v_add_f32_e32 v114, 1.0, v114
	v_rcp_f32_e32 v155, v115
	v_add_f32_e32 v115, 1.0, v121
	v_rcp_f32_e32 v114, v114
	v_rcp_f32_e32 v115, v115
	v_add_f32_e32 v58, v58, v103
	v_max_f32_e32 v58, 0x179abe15, v58
	v_pk_add_f32 v[36:37], v[36:37], -1.0 op_sel_hi:[1,0]
	v_mul_f32_e32 v121, 0xbf1b4598, v155
	v_rsq_f32_e32 v58, v58
	v_pk_add_f32 v[36:37], v[36:37], 1.0 op_sel_hi:[1,0]
	v_mul_f32_e32 v121, 0x3fb8aa3b, v121
	v_pk_mul_f32 v[50:51], v[50:51], v[114:115]
	v_pk_mul_f32 v[114:115], v[116:117], v[36:37]
	v_exp_f32_e32 v155, v121
	v_rcp_f32_e32 v36, v114
	v_rcp_f32_e32 v37, v115
	v_pk_mul_f32 v[148:149], v[148:149], v[58:59] op_sel_hi:[1,0]
	v_mad_i64_i32 v[120:121], s[10:11], v120, s23, v[56:57]
	v_pk_mul_f32 v[178:179], v[116:117], v[148:149]
	v_pk_mul_f32 v[116:117], v[122:123], v[148:149]
	v_pk_mul_f32 v[148:149], v[152:153], v[58:59] op_sel_hi:[1,0]
	v_pk_mul_f32 v[122:123], v[116:117], v[36:37]
	v_pk_add_f32 v[116:117], v[154:155], -1.0 op_sel_hi:[1,0]
	v_pk_mul_f32 v[36:37], v[118:119], v[36:37]
	v_pk_add_f32 v[116:117], v[116:117], 1.0 op_sel_hi:[1,0]
	v_lshlrev_b32_e32 v54, 16, v42
	v_pk_mul_f32 v[116:117], v[112:113], v[116:117]
	v_and_b32_e32 v55, 0xffff0000, v42
	v_rcp_f32_e32 v118, v116
	v_rcp_f32_e32 v119, v117
	v_lshlrev_b32_e32 v42, 16, v43
	v_and_b32_e32 v43, 0xffff0000, v43
	v_pk_mul_f32 v[38:39], v[38:39], v[114:115]
	v_pk_mul_f32 v[126:127], v[126:127], v[148:149]
	v_pk_mul_f32 v[124:125], v[124:125], v[116:117]
	v_lshlrev_b64 v[120:121], 1, v[120:121]
	v_pk_add_f32 v[104:105], v[104:105], v[54:55] neg_lo:[0,1] neg_hi:[0,1]
	v_pk_add_f32 v[44:45], v[44:45], v[42:43] neg_lo:[0,1] neg_hi:[0,1]
	v_pk_mul_f32 v[126:127], v[126:127], v[118:119]
	v_pk_mul_f32 v[118:119], v[150:151], v[118:119]
	v_cvt_pk_bf16_f32 v38, v38, v39
	v_cvt_pk_bf16_f32 v39, v124, v125
	v_lshl_add_u64 v[124:125], s[74:75], 0, v[120:121]
	v_pk_fma_f32 v[104:105], v[0:1], v[104:105], v[54:55]
	v_pk_fma_f32 v[44:45], v[2:3], v[44:45], v[42:43]
	global_store_dwordx2 v[124:125], v[38:39], off nt
	v_cvt_pk_bf16_f32 v36, v36, v37
	v_cvt_pk_bf16_f32 v37, v118, v119
	v_lshl_add_u64 v[38:39], s[76:77], 0, v[120:121]
	v_pk_mul_f32 v[112:113], v[112:113], v[148:149]
	global_store_dwordx2 v[38:39], v[36:37], off nt
	v_cvt_pk_bf16_f32 v36, v104, v105
	v_cvt_pk_bf16_f32 v37, v44, v45
	v_lshl_add_u64 v[38:39], s[78:79], 0, v[120:121]
	global_store_dwordx2 v[38:39], v[36:37], off nt
	v_cvt_pk_bf16_f32 v36, v178, v179
	v_cvt_pk_bf16_f32 v37, v112, v113
	v_lshl_add_u64 v[38:39], s[80:81], 0, v[120:121]
	global_store_dwordx2 v[38:39], v[36:37], off nt
	v_cvt_pk_bf16_f32 v36, v122, v123
	v_cvt_pk_bf16_f32 v37, v126, v127
	v_lshl_add_u64 v[38:39], s[82:83], 0, v[120:121]
	global_store_dwordx2 v[38:39], v[36:37], off nt
	v_cvt_pk_bf16_f32 v36, v108, v109
	v_cvt_pk_bf16_f32 v37, v50, v51
	v_lshl_add_u64 v[38:39], s[84:85], 0, v[120:121]
	v_add_u32_e32 v122, 2, v102
	global_store_dwordx2 v[38:39], v[36:37], off nt
	v_mad_i64_i32 v[36:37], s[10:11], v122, s22, v[60:61]
	v_add_co_u32_e32 v36, vcc, s2, v36
	v_ashrrev_i32_e32 v123, 31, v122
	s_nop 0
	v_addc_co_u32_e32 v37, vcc, 0, v37, vcc
	s_waitcnt vmcnt(16)
	v_mov_b64_e32 v[44:45], v[234:235]
	v_mov_b64_e32 v[50:51], v[236:237]
	v_mov_b64_e32 v[154:155], v[238:239]
	v_mov_b64_e32 v[118:119], v[240:241]
	v_add_u32_e32 v242, 4, v102
	v_mad_i64_i32 v[242:243], s[26:27], v242, s22, v[60:61]
	global_load_dwordx2 v[234:235], v[242:243], off
	global_load_dwordx2 v[236:237], v[242:243], off offset:2048
	v_add_co_u32_e32 v244, vcc, s2, v242
	s_nop 1
	v_addc_co_u32_e32 v245, vcc, 0, v243, vcc
	global_load_dwordx2 v[238:239], v[244:245], off
	global_load_dwordx2 v[240:241], v[244:245], off offset:2048
	ds_read2st64_b64 v[36:39], v168 offset0:16 offset1:80
	s_waitcnt lgkmcnt(0)
	v_lshlrev_b32_e32 v58, 16, v38
	v_and_b32_e32 v38, 0xffff0000, v38
	v_lshlrev_b32_e32 v103, 16, v39
	v_and_b32_e32 v126, 0xffff0000, v39
	v_add_f32_e32 v39, v12, v58
	v_mul_f32_e32 v39, 0xbfb8aa3b, v39
	v_add_f32_e32 v38, v13, v38
	v_exp_f32_e32 v39, v39
	v_mul_f32_e32 v38, 0xbfb8aa3b, v38
	v_exp_f32_e32 v58, v38
	v_add_f32_e32 v38, 1.0, v39
	v_rcp_f32_e32 v120, v38
	v_lshlrev_b32_e32 v108, 16, v44
	v_and_b32_e32 v109, 0xffff0000, v44
	v_pk_add_f32 v[38:39], v[52:53], v[108:109] neg_lo:[0,1] neg_hi:[0,1]
	v_add_f32_e32 v52, 1.0, v58
	v_add_f32_e32 v58, v14, v103
	v_mul_f32_e32 v58, 0xbfb8aa3b, v58
	v_add_f32_e32 v103, v15, v126
	v_exp_f32_e32 v58, v58
	v_mul_f32_e32 v103, 0xbfb8aa3b, v103
	v_exp_f32_e32 v103, v103
	v_rcp_f32_e32 v121, v52
	v_add_f32_e32 v58, 1.0, v58
	v_rcp_f32_e32 v148, v58
	v_add_f32_e32 v58, 1.0, v103
	v_rcp_f32_e32 v149, v58
	v_lshlrev_b32_e32 v44, 16, v45
	v_and_b32_e32 v45, 0xffff0000, v45
	v_lshlrev_b32_e32 v112, 16, v50
	v_and_b32_e32 v113, 0xffff0000, v50
	v_lshlrev_b32_e32 v50, 16, v51
	v_and_b32_e32 v51, 0xffff0000, v51
	v_pk_add_f32 v[52:53], v[110:111], v[112:113] neg_lo:[0,1] neg_hi:[0,1]
	v_pk_add_f32 v[40:41], v[40:41], v[44:45] neg_lo:[0,1] neg_hi:[0,1]
	v_pk_fma_f32 v[52:53], v[20:21], v[52:53], v[112:113]
	v_pk_add_f32 v[104:105], v[120:121], -1.0 op_sel_hi:[1,0]
	v_pk_fma_f32 v[126:127], v[18:19], v[40:41], v[44:45]
	v_pk_add_f32 v[40:41], v[46:47], v[50:51] neg_lo:[0,1] neg_hi:[0,1]
	v_pk_fma_f32 v[104:105], v[28:29], v[104:105], 1.0 op_sel_hi:[1,1,0]
	v_pk_mul_f32 v[150:151], v[24:25], v[52:53]
	v_pk_fma_f32 v[40:41], v[22:23], v[40:41], v[50:51]
	v_pk_add_f32 v[46:47], v[148:149], -1.0 op_sel_hi:[1,0]
	v_pk_fma_f32 v[38:39], v[16:17], v[38:39], v[108:109]
	v_pk_mul_f32 v[124:125], v[52:53], v[104:105]
	v_pk_mul_f32 v[52:53], v[150:151], v[150:151]
	v_pk_fma_f32 v[46:47], v[30:31], v[46:47], 1.0 op_sel_hi:[1,1,0]
	v_pk_mul_f32 v[152:153], v[26:27], v[40:41]
	v_pk_mul_f32 v[104:105], v[38:39], v[124:125]
	v_pk_mul_f32 v[46:47], v[40:41], v[46:47]
	v_pk_mul_f32 v[40:41], v[152:153], v[152:153]
	v_add_f32_e32 v52, v52, v53
	v_fma_f32 v110, v32, v104, 0
	v_add_f32_e32 v40, v52, v40
	v_fmac_f32_e32 v110, v33, v105
	v_pk_mul_f32 v[104:105], v[126:127], v[46:47]
	v_add_f32_e32 v40, v41, v40
	v_fmac_f32_e32 v110, v34, v104
	v_fmac_f32_e32 v110, v35, v105
	v_add_f32_dpp v40, v40, v40 quad_perm:[1,0,3,2] row_mask:0xf bank_mask:0xf bound_ctrl:1
	s_nop 1
	v_add_f32_dpp v40, v40, v40 quad_perm:[2,3,0,1] row_mask:0xf bank_mask:0xf bound_ctrl:1
	s_nop 1
	v_add_f32_dpp v58, v40, v40 row_half_mirror row_mask:0xf bank_mask:0xf bound_ctrl:1
	v_add_f32_dpp v40, v110, v110 quad_perm:[1,0,3,2] row_mask:0xf bank_mask:0xf bound_ctrl:1
	s_nop 0
	v_mov_b32_dpp v103, v58 row_mirror row_mask:0xf bank_mask:0xf bound_ctrl:1
	v_add_f32_dpp v40, v40, v40 quad_perm:[2,3,0,1] row_mask:0xf bank_mask:0xf bound_ctrl:1
	s_nop 1
	v_add_f32_dpp v40, v40, v40 row_half_mirror row_mask:0xf bank_mask:0xf bound_ctrl:1
	s_nop 1
	v_mov_b32_dpp v41, v40 row_mirror row_mask:0xf bank_mask:0xf bound_ctrl:1
	s_and_saveexec_b64 s[10:11], s[6:7]
	s_cbranch_execz .LBB0_201
	v_lshlrev_b64 v[52:53], 6, v[122:123]
	v_lshl_add_u64 v[52:53], v[98:99], 0, v[52:53]
	v_add_f32_e32 v40, v40, v41
	global_store_dword v[52:53], v40, off nt
.LBB0_201:
	s_or_b64 exec, exec, s[10:11]
	v_lshlrev_b32_e32 v52, 16, v36
	v_add_f32_e32 v52, v8, v52
	v_mul_f32_e32 v52, 0xbfb8aa3b, v52
	v_exp_f32_e32 v123, v52
	v_lshlrev_b32_e32 v110, 16, v118
	v_and_b32_e32 v111, 0xffff0000, v118
	v_pk_add_f32 v[106:107], v[106:107], v[110:111] neg_lo:[0,1] neg_hi:[0,1]
	v_add_f32_e32 v118, 1.0, v123
	v_rcp_f32_e32 v118, v118
	v_lshlrev_b32_e32 v52, 16, v119
	v_and_b32_e32 v53, 0xffff0000, v119
	v_and_b32_e32 v119, 0xffff0000, v36
	v_pk_fma_f32 v[106:107], v[4:5], v[106:107], v[110:111]
	v_lshlrev_b32_e32 v40, 16, v155
	v_and_b32_e32 v41, 0xffff0000, v155
	v_lshlrev_b32_e32 v123, 16, v37
	v_and_b32_e32 v155, 0xffff0000, v37
	v_mul_f32_e32 v36, 0xbf1b4598, v118
	v_mul_f32_e32 v37, 0xbfb8aa3b, v106
	v_add_f32_e32 v118, v9, v119
	v_exp_f32_e32 v37, v37
	v_mul_f32_e32 v118, 0xbfb8aa3b, v118
	v_exp_f32_e32 v119, v118
	v_add_f32_e32 v123, v10, v123
	v_add_f32_e32 v37, 1.0, v37
	v_rcp_f32_e32 v118, v37
	v_add_f32_e32 v37, 1.0, v119
	v_mul_f32_e32 v119, 0xbfb8aa3b, v107
	v_mul_f32_e32 v123, 0xbfb8aa3b, v123
	v_exp_f32_e32 v119, v119
	v_exp_f32_e32 v123, v123
	v_rcp_f32_e32 v37, v37
	v_pk_add_f32 v[48:49], v[48:49], v[52:53] neg_lo:[0,1] neg_hi:[0,1]
	v_add_f32_e32 v119, 1.0, v119
	v_add_f32_e32 v123, 1.0, v123
	v_rcp_f32_e32 v119, v119
	v_rcp_f32_e32 v123, v123
	v_pk_fma_f32 v[48:49], v[6:7], v[48:49], v[52:53]
	v_lshlrev_b32_e32 v104, 16, v154
	v_pk_mul_f32 v[106:107], v[106:107], v[118:119]
	v_mul_f32_e32 v118, 0xbf1b4598, v123
	v_add_f32_e32 v119, v11, v155
	v_mul_f32_e32 v118, 0x3fb8aa3b, v118
	v_mul_f32_e32 v119, 0xbfb8aa3b, v119
	v_and_b32_e32 v105, 0xffff0000, v154
	v_exp_f32_e32 v154, v118
	v_mul_f32_e32 v118, 0xbfb8aa3b, v48
	v_exp_f32_e32 v119, v119
	v_mul_f32_e32 v123, 0xbfb8aa3b, v49
	v_exp_f32_e32 v118, v118
	v_exp_f32_e32 v123, v123
	v_mul_f32_e32 v37, 0xbf1b4598, v37
	v_mul_f32_e32 v36, 0x3fb8aa3b, v36
	v_mul_f32_e32 v37, 0x3fb8aa3b, v37
	v_exp_f32_e32 v36, v36
	v_exp_f32_e32 v37, v37
	v_add_f32_e32 v119, 1.0, v119
	v_add_f32_e32 v118, 1.0, v118
	v_rcp_f32_e32 v155, v119
	v_add_f32_e32 v119, 1.0, v123
	v_rcp_f32_e32 v118, v118
	v_rcp_f32_e32 v119, v119
	v_add_f32_e32 v58, v58, v103
	v_max_f32_e32 v58, 0x179abe15, v58
	v_pk_add_f32 v[36:37], v[36:37], -1.0 op_sel_hi:[1,0]
	v_mul_f32_e32 v123, 0xbf1b4598, v155
	v_rsq_f32_e32 v58, v58
	v_pk_add_f32 v[36:37], v[36:37], 1.0 op_sel_hi:[1,0]
	v_mul_f32_e32 v123, 0x3fb8aa3b, v123
	v_pk_mul_f32 v[48:49], v[48:49], v[118:119]
	v_pk_mul_f32 v[118:119], v[114:115], v[36:37]
	v_exp_f32_e32 v155, v123
	v_rcp_f32_e32 v36, v118
	v_rcp_f32_e32 v37, v119
	v_pk_mul_f32 v[150:151], v[150:151], v[58:59] op_sel_hi:[1,0]
	v_pk_mul_f32 v[152:153], v[152:153], v[58:59] op_sel_hi:[1,0]
	v_pk_mul_f32 v[120:121], v[120:121], v[150:151]
	v_pk_mul_f32 v[114:115], v[114:115], v[150:151]
	v_pk_mul_f32 v[150:151], v[120:121], v[36:37]
	v_pk_add_f32 v[120:121], v[154:155], -1.0 op_sel_hi:[1,0]
	v_pk_mul_f32 v[36:37], v[124:125], v[36:37]
	v_pk_add_f32 v[120:121], v[120:121], 1.0 op_sel_hi:[1,0]
	v_mad_i64_i32 v[122:123], s[10:11], v122, s23, v[56:57]
	v_pk_mul_f32 v[120:121], v[116:117], v[120:121]
	v_pk_mul_f32 v[38:39], v[38:39], v[118:119]
	v_rcp_f32_e32 v124, v120
	v_rcp_f32_e32 v125, v121
	v_pk_mul_f32 v[148:149], v[148:149], v[152:153]
	v_pk_mul_f32 v[126:127], v[126:127], v[120:121]
	v_lshlrev_b64 v[122:123], 1, v[122:123]
	v_pk_add_f32 v[54:55], v[54:55], v[104:105] neg_lo:[0,1] neg_hi:[0,1]
	v_pk_add_f32 v[42:43], v[42:43], v[40:41] neg_lo:[0,1] neg_hi:[0,1]
	v_pk_mul_f32 v[148:149], v[148:149], v[124:125]
	v_pk_mul_f32 v[46:47], v[46:47], v[124:125]
	v_cvt_pk_bf16_f32 v38, v38, v39
	v_cvt_pk_bf16_f32 v39, v126, v127
	v_lshl_add_u64 v[124:125], s[74:75], 0, v[122:123]
	v_pk_fma_f32 v[54:55], v[0:1], v[54:55], v[104:105]
	v_pk_fma_f32 v[42:43], v[2:3], v[42:43], v[40:41]
	global_store_dwordx2 v[124:125], v[38:39], off nt
	v_cvt_pk_bf16_f32 v36, v36, v37
	v_cvt_pk_bf16_f32 v37, v46, v47
	v_lshl_add_u64 v[38:39], s[76:77], 0, v[122:123]
	v_pk_mul_f32 v[116:117], v[116:117], v[152:153]
	global_store_dwordx2 v[38:39], v[36:37], off nt
	v_cvt_pk_bf16_f32 v36, v54, v55
	v_cvt_pk_bf16_f32 v37, v42, v43
	v_lshl_add_u64 v[38:39], s[78:79], 0, v[122:123]
	global_store_dwordx2 v[38:39], v[36:37], off nt
	v_cvt_pk_bf16_f32 v36, v114, v115
	v_cvt_pk_bf16_f32 v37, v116, v117
	v_lshl_add_u64 v[38:39], s[80:81], 0, v[122:123]
	global_store_dwordx2 v[38:39], v[36:37], off nt
	v_cvt_pk_bf16_f32 v36, v150, v151
	v_cvt_pk_bf16_f32 v37, v148, v149
	v_lshl_add_u64 v[38:39], s[82:83], 0, v[122:123]
	global_store_dwordx2 v[38:39], v[36:37], off nt
	v_cvt_pk_bf16_f32 v36, v106, v107
	v_cvt_pk_bf16_f32 v37, v48, v49
	v_lshl_add_u64 v[38:39], s[84:85], 0, v[122:123]
	v_add_u32_e32 v122, 3, v102
	global_store_dwordx2 v[38:39], v[36:37], off nt
	v_mad_i64_i32 v[36:37], s[10:11], v122, s22, v[60:61]
	v_add_co_u32_e32 v36, vcc, s2, v36
	v_ashrrev_i32_e32 v123, 31, v122
	s_nop 0
	v_addc_co_u32_e32 v37, vcc, 0, v37, vcc
	s_waitcnt vmcnt(16)
	v_mov_b64_e32 v[46:47], v[246:247]
	v_mov_b64_e32 v[48:49], v[248:249]
	v_mov_b64_e32 v[42:43], v[250:251]
	v_mov_b64_e32 v[116:117], v[254:255]
	v_add_u32_e32 v242, 5, v102
	v_mad_i64_i32 v[242:243], s[26:27], v242, s22, v[60:61]
	global_load_dwordx2 v[246:247], v[242:243], off
	global_load_dwordx2 v[248:249], v[242:243], off offset:2048
	v_add_co_u32_e32 v244, vcc, s2, v242
	s_nop 1
	v_addc_co_u32_e32 v245, vcc, 0, v243, vcc
	global_load_dwordx2 v[250:251], v[244:245], off
	global_load_dwordx2 v[254:255], v[244:245], off offset:2048
	ds_read2st64_b64 v[36:39], v169 offset0:16 offset1:80
	s_waitcnt lgkmcnt(0)
	v_lshlrev_b32_e32 v54, 16, v38
	v_and_b32_e32 v38, 0xffff0000, v38
	v_lshlrev_b32_e32 v58, 16, v39
	v_and_b32_e32 v103, 0xffff0000, v39
	v_add_f32_e32 v39, v12, v54
	v_add_f32_e32 v38, v13, v38
	v_mul_f32_e32 v39, 0xbfb8aa3b, v39
	v_mul_f32_e32 v38, 0xbfb8aa3b, v38
	v_exp_f32_e32 v39, v39
	v_exp_f32_e32 v54, v38
	v_add_f32_e32 v58, v14, v58
	v_mul_f32_e32 v58, 0xbfb8aa3b, v58
	v_add_f32_e32 v103, v15, v103
	v_add_f32_e32 v38, 1.0, v39
	v_add_f32_e32 v54, 1.0, v54
	v_exp_f32_e32 v58, v58
	v_mul_f32_e32 v103, 0xbfb8aa3b, v103
	v_rcp_f32_e32 v124, v38
	v_rcp_f32_e32 v125, v54
	v_exp_f32_e32 v103, v103
	v_add_f32_e32 v58, 1.0, v58
	v_rcp_f32_e32 v126, v58
	v_add_f32_e32 v58, 1.0, v103
	v_rcp_f32_e32 v127, v58
	v_lshlrev_b32_e32 v106, 16, v46
	v_and_b32_e32 v107, 0xffff0000, v46
	v_lshlrev_b32_e32 v114, 16, v48
	v_and_b32_e32 v115, 0xffff0000, v48
	v_pk_add_f32 v[38:39], v[108:109], v[106:107] neg_lo:[0,1] neg_hi:[0,1]
	v_pk_add_f32 v[54:55], v[112:113], v[114:115] neg_lo:[0,1] neg_hi:[0,1]
	v_pk_add_f32 v[108:109], v[124:125], -1.0 op_sel_hi:[1,0]
	v_pk_fma_f32 v[54:55], v[20:21], v[54:55], v[114:115]
	v_pk_fma_f32 v[108:109], v[28:29], v[108:109], 1.0 op_sel_hi:[1,1,0]
	v_pk_fma_f32 v[38:39], v[16:17], v[38:39], v[106:107]
	v_pk_mul_f32 v[108:109], v[54:55], v[108:109]
	v_lshlrev_b32_e32 v48, 16, v49
	v_and_b32_e32 v49, 0xffff0000, v49
	v_pk_mul_f32 v[112:113], v[38:39], v[108:109]
	v_pk_add_f32 v[50:51], v[50:51], v[48:49] neg_lo:[0,1] neg_hi:[0,1]
	v_fma_f32 v154, v32, v112, 0
	v_pk_mul_f32 v[148:149], v[24:25], v[54:55]
	v_fmac_f32_e32 v154, v33, v113
	v_pk_fma_f32 v[50:51], v[22:23], v[50:51], v[48:49]
	v_pk_add_f32 v[112:113], v[126:127], -1.0 op_sel_hi:[1,0]
	v_lshlrev_b32_e32 v46, 16, v47
	v_and_b32_e32 v47, 0xffff0000, v47
	v_pk_mul_f32 v[54:55], v[148:149], v[148:149]
	v_pk_fma_f32 v[112:113], v[30:31], v[112:113], 1.0 op_sel_hi:[1,1,0]
	v_pk_mul_f32 v[152:153], v[26:27], v[50:51]
	v_pk_add_f32 v[44:45], v[44:45], v[46:47] neg_lo:[0,1] neg_hi:[0,1]
	v_pk_mul_f32 v[150:151], v[50:51], v[112:113]
	v_pk_mul_f32 v[50:51], v[152:153], v[152:153]
	v_add_f32_e32 v54, v54, v55
	v_pk_fma_f32 v[44:45], v[18:19], v[44:45], v[46:47]
	v_add_f32_e32 v50, v54, v50
	v_pk_mul_f32 v[112:113], v[44:45], v[150:151]
	v_add_f32_e32 v50, v51, v50
	v_fmac_f32_e32 v154, v34, v112
	v_fmac_f32_e32 v154, v35, v113
	v_add_f32_dpp v50, v50, v50 quad_perm:[1,0,3,2] row_mask:0xf bank_mask:0xf bound_ctrl:1
	s_nop 1
	v_add_f32_dpp v50, v50, v50 quad_perm:[2,3,0,1] row_mask:0xf bank_mask:0xf bound_ctrl:1
	s_nop 1
	v_add_f32_dpp v58, v50, v50 row_half_mirror row_mask:0xf bank_mask:0xf bound_ctrl:1
	v_add_f32_dpp v50, v154, v154 quad_perm:[1,0,3,2] row_mask:0xf bank_mask:0xf bound_ctrl:1
	s_nop 0
	v_mov_b32_dpp v103, v58 row_mirror row_mask:0xf bank_mask:0xf bound_ctrl:1
	v_add_f32_dpp v50, v50, v50 quad_perm:[2,3,0,1] row_mask:0xf bank_mask:0xf bound_ctrl:1
	s_nop 1
	v_add_f32_dpp v50, v50, v50 row_half_mirror row_mask:0xf bank_mask:0xf bound_ctrl:1
	s_nop 1
	v_mov_b32_dpp v51, v50 row_mirror row_mask:0xf bank_mask:0xf bound_ctrl:1
	s_and_saveexec_b64 s[10:11], s[6:7]
	s_cbranch_execz .LBB0_203
	v_lshlrev_b64 v[54:55], 6, v[122:123]
	v_lshl_add_u64 v[54:55], v[98:99], 0, v[54:55]
	v_add_f32_e32 v50, v50, v51
	global_store_dword v[54:55], v50, off nt
.LBB0_203:
	s_or_b64 exec, exec, s[10:11]
	v_lshlrev_b32_e32 v50, 16, v36
	v_add_f32_e32 v50, v8, v50
	v_mul_f32_e32 v50, 0xbfb8aa3b, v50
	v_exp_f32_e32 v123, v50
	v_lshlrev_b32_e32 v112, 16, v116
	v_and_b32_e32 v113, 0xffff0000, v116
	v_pk_add_f32 v[110:111], v[110:111], v[112:113] neg_lo:[0,1] neg_hi:[0,1]
	v_add_f32_e32 v116, 1.0, v123
	v_rcp_f32_e32 v116, v116
	v_lshlrev_b32_e32 v50, 16, v117
	v_and_b32_e32 v51, 0xffff0000, v117
	v_and_b32_e32 v117, 0xffff0000, v36
	v_pk_fma_f32 v[110:111], v[4:5], v[110:111], v[112:113]
	v_lshlrev_b32_e32 v123, 16, v37
	v_and_b32_e32 v155, 0xffff0000, v37
	v_mul_f32_e32 v36, 0xbf1b4598, v116
	v_mul_f32_e32 v37, 0xbfb8aa3b, v110
	v_add_f32_e32 v116, v9, v117
	v_exp_f32_e32 v37, v37
	v_mul_f32_e32 v116, 0xbfb8aa3b, v116
	v_exp_f32_e32 v117, v116
	v_add_f32_e32 v123, v10, v123
	v_add_f32_e32 v37, 1.0, v37
	v_rcp_f32_e32 v116, v37
	v_add_f32_e32 v37, 1.0, v117
	v_mul_f32_e32 v117, 0xbfb8aa3b, v111
	v_mul_f32_e32 v123, 0xbfb8aa3b, v123
	v_exp_f32_e32 v117, v117
	v_exp_f32_e32 v123, v123
	v_rcp_f32_e32 v37, v37
	v_pk_add_f32 v[52:53], v[52:53], v[50:51] neg_lo:[0,1] neg_hi:[0,1]
	v_add_f32_e32 v117, 1.0, v117
	v_add_f32_e32 v123, 1.0, v123
	v_rcp_f32_e32 v117, v117
	v_rcp_f32_e32 v123, v123
	v_pk_fma_f32 v[52:53], v[6:7], v[52:53], v[50:51]
	v_mul_f32_e32 v37, 0xbf1b4598, v37
	v_pk_mul_f32 v[110:111], v[110:111], v[116:117]
	v_mul_f32_e32 v116, 0xbf1b4598, v123
	v_add_f32_e32 v117, v11, v155
	v_mul_f32_e32 v116, 0x3fb8aa3b, v116
	v_mul_f32_e32 v117, 0xbfb8aa3b, v117
	v_exp_f32_e32 v154, v116
	v_mul_f32_e32 v116, 0xbfb8aa3b, v52
	v_exp_f32_e32 v117, v117
	v_mul_f32_e32 v123, 0xbfb8aa3b, v53
	v_exp_f32_e32 v116, v116
	v_exp_f32_e32 v123, v123
	v_mul_f32_e32 v36, 0x3fb8aa3b, v36
	v_mul_f32_e32 v37, 0x3fb8aa3b, v37
	v_exp_f32_e32 v36, v36
	v_exp_f32_e32 v37, v37
	v_add_f32_e32 v117, 1.0, v117
	v_add_f32_e32 v116, 1.0, v116
	v_rcp_f32_e32 v155, v117
	v_add_f32_e32 v117, 1.0, v123
	v_rcp_f32_e32 v116, v116
	v_rcp_f32_e32 v117, v117
	v_add_f32_e32 v58, v58, v103
	v_max_f32_e32 v58, 0x179abe15, v58
	v_pk_add_f32 v[36:37], v[36:37], -1.0 op_sel_hi:[1,0]
	v_mul_f32_e32 v123, 0xbf1b4598, v155
	v_rsq_f32_e32 v58, v58
	v_pk_add_f32 v[36:37], v[36:37], 1.0 op_sel_hi:[1,0]
	v_mul_f32_e32 v123, 0x3fb8aa3b, v123
	v_pk_mul_f32 v[52:53], v[52:53], v[116:117]
	v_pk_mul_f32 v[116:117], v[118:119], v[36:37]
	v_exp_f32_e32 v155, v123
	v_rcp_f32_e32 v36, v116
	v_rcp_f32_e32 v37, v117
	v_pk_mul_f32 v[148:149], v[148:149], v[58:59] op_sel_hi:[1,0]
	v_pk_mul_f32 v[38:39], v[38:39], v[116:117]
	v_pk_mul_f32 v[178:179], v[118:119], v[148:149]
	v_pk_mul_f32 v[118:119], v[124:125], v[148:149]
	v_pk_mul_f32 v[148:149], v[152:153], v[58:59] op_sel_hi:[1,0]
	v_pk_mul_f32 v[124:125], v[118:119], v[36:37]
	v_pk_mul_f32 v[36:37], v[108:109], v[36:37]
	v_pk_add_f32 v[108:109], v[154:155], -1.0 op_sel_hi:[1,0]
	v_mad_i64_i32 v[122:123], s[10:11], v122, s23, v[56:57]
	v_pk_add_f32 v[108:109], v[108:109], 1.0 op_sel_hi:[1,0]
	v_lshlrev_b32_e32 v54, 16, v42
	v_pk_mul_f32 v[118:119], v[120:121], v[108:109]
	v_and_b32_e32 v55, 0xffff0000, v42
	v_rcp_f32_e32 v108, v118
	v_rcp_f32_e32 v109, v119
	v_pk_mul_f32 v[44:45], v[44:45], v[118:119]
	v_lshlrev_b32_e32 v42, 16, v43
	v_and_b32_e32 v43, 0xffff0000, v43
	v_pk_mul_f32 v[126:127], v[126:127], v[148:149]
	v_cvt_pk_bf16_f32 v38, v38, v39
	v_cvt_pk_bf16_f32 v39, v44, v45
	v_lshlrev_b64 v[44:45], 1, v[122:123]
	v_pk_add_f32 v[104:105], v[104:105], v[54:55] neg_lo:[0,1] neg_hi:[0,1]
	v_pk_add_f32 v[40:41], v[40:41], v[42:43] neg_lo:[0,1] neg_hi:[0,1]
	v_pk_mul_f32 v[126:127], v[126:127], v[108:109]
	v_pk_mul_f32 v[108:109], v[150:151], v[108:109]
	v_lshl_add_u64 v[122:123], s[74:75], 0, v[44:45]
	v_pk_fma_f32 v[104:105], v[0:1], v[104:105], v[54:55]
	v_pk_fma_f32 v[40:41], v[2:3], v[40:41], v[42:43]
	global_store_dwordx2 v[122:123], v[38:39], off nt
	v_cvt_pk_bf16_f32 v36, v36, v37
	v_cvt_pk_bf16_f32 v37, v108, v109
	v_lshl_add_u64 v[38:39], s[76:77], 0, v[44:45]
	v_pk_mul_f32 v[120:121], v[120:121], v[148:149]
	global_store_dwordx2 v[38:39], v[36:37], off nt
	v_cvt_pk_bf16_f32 v36, v104, v105
	v_cvt_pk_bf16_f32 v37, v40, v41
	v_lshl_add_u64 v[38:39], s[78:79], 0, v[44:45]
	global_store_dwordx2 v[38:39], v[36:37], off nt
	v_cvt_pk_bf16_f32 v36, v178, v179
	v_cvt_pk_bf16_f32 v37, v120, v121
	v_lshl_add_u64 v[38:39], s[80:81], 0, v[44:45]
	global_store_dwordx2 v[38:39], v[36:37], off nt
	v_cvt_pk_bf16_f32 v36, v124, v125
	v_cvt_pk_bf16_f32 v37, v126, v127
	v_lshl_add_u64 v[38:39], s[82:83], 0, v[44:45]
	global_store_dwordx2 v[38:39], v[36:37], off nt
	v_cvt_pk_bf16_f32 v36, v110, v111
	v_cvt_pk_bf16_f32 v37, v52, v53
	v_lshl_add_u64 v[38:39], s[84:85], 0, v[44:45]
	v_add_u32_e32 v122, 4, v102
	global_store_dwordx2 v[38:39], v[36:37], off nt
	v_mad_i64_i32 v[36:37], s[10:11], v122, s22, v[60:61]
	v_add_co_u32_e32 v36, vcc, s2, v36
	v_ashrrev_i32_e32 v123, 31, v122
	s_nop 0
	v_addc_co_u32_e32 v37, vcc, 0, v37, vcc
	s_waitcnt vmcnt(16)
	v_mov_b64_e32 v[44:45], v[234:235]
	v_mov_b64_e32 v[52:53], v[236:237]
	v_mov_b64_e32 v[40:41], v[238:239]
	v_mov_b64_e32 v[120:121], v[240:241]
	v_add_u32_e32 v242, 6, v102
	v_mad_i64_i32 v[242:243], s[26:27], v242, s22, v[60:61]
	global_load_dwordx2 v[234:235], v[242:243], off
	global_load_dwordx2 v[236:237], v[242:243], off offset:2048
	v_add_co_u32_e32 v244, vcc, s2, v242
	s_nop 1
	v_addc_co_u32_e32 v245, vcc, 0, v243, vcc
	global_load_dwordx2 v[238:239], v[244:245], off
	global_load_dwordx2 v[240:241], v[244:245], off offset:2048
	ds_read2st64_b64 v[36:39], v170 offset0:16 offset1:80
	s_waitcnt lgkmcnt(0)
	v_lshlrev_b32_e32 v58, 16, v38
	v_and_b32_e32 v38, 0xffff0000, v38
	v_add_f32_e32 v38, v13, v38
	v_mul_f32_e32 v38, 0xbfb8aa3b, v38
	v_lshlrev_b32_e32 v103, 16, v39
	v_and_b32_e32 v126, 0xffff0000, v39
	v_add_f32_e32 v39, v12, v58
	v_exp_f32_e32 v58, v38
	v_mul_f32_e32 v39, 0xbfb8aa3b, v39
	v_exp_f32_e32 v39, v39
	v_add_f32_e32 v58, 1.0, v58
	v_rcp_f32_e32 v125, v58
	v_add_f32_e32 v58, v14, v103
	v_mul_f32_e32 v58, 0xbfb8aa3b, v58
	v_add_f32_e32 v103, v15, v126
	v_exp_f32_e32 v58, v58
	v_mul_f32_e32 v103, 0xbfb8aa3b, v103
	v_exp_f32_e32 v103, v103
	v_add_f32_e32 v38, 1.0, v39
	v_add_f32_e32 v58, 1.0, v58
	v_rcp_f32_e32 v124, v38
	v_rcp_f32_e32 v148, v58
	v_add_f32_e32 v58, 1.0, v103
	v_rcp_f32_e32 v149, v58
	v_lshlrev_b32_e32 v108, 16, v44
	v_and_b32_e32 v109, 0xffff0000, v44
	v_lshlrev_b32_e32 v44, 16, v45
	v_and_b32_e32 v45, 0xffff0000, v45
	v_lshlrev_b32_e32 v110, 16, v52
	v_and_b32_e32 v111, 0xffff0000, v52
	v_lshlrev_b32_e32 v52, 16, v53
	v_and_b32_e32 v53, 0xffff0000, v53
	v_pk_add_f32 v[104:105], v[114:115], v[110:111] neg_lo:[0,1] neg_hi:[0,1]
	v_pk_add_f32 v[46:47], v[46:47], v[44:45] neg_lo:[0,1] neg_hi:[0,1]
	v_pk_add_f32 v[38:39], v[106:107], v[108:109] neg_lo:[0,1] neg_hi:[0,1]
	v_pk_fma_f32 v[104:105], v[20:21], v[104:105], v[110:111]
	v_pk_add_f32 v[106:107], v[124:125], -1.0 op_sel_hi:[1,0]
	v_pk_fma_f32 v[126:127], v[18:19], v[46:47], v[44:45]
	v_pk_add_f32 v[46:47], v[48:49], v[52:53] neg_lo:[0,1] neg_hi:[0,1]
	v_pk_fma_f32 v[106:107], v[28:29], v[106:107], 1.0 op_sel_hi:[1,1,0]
	v_pk_mul_f32 v[150:151], v[24:25], v[104:105]
	v_pk_fma_f32 v[46:47], v[22:23], v[46:47], v[52:53]
	v_pk_add_f32 v[48:49], v[148:149], -1.0 op_sel_hi:[1,0]
	v_pk_fma_f32 v[38:39], v[16:17], v[38:39], v[108:109]
	v_pk_mul_f32 v[106:107], v[104:105], v[106:107]
	v_pk_mul_f32 v[104:105], v[150:151], v[150:151]
	v_pk_fma_f32 v[48:49], v[30:31], v[48:49], 1.0 op_sel_hi:[1,1,0]
	v_pk_mul_f32 v[152:153], v[26:27], v[46:47]
	v_pk_mul_f32 v[114:115], v[38:39], v[106:107]
	v_pk_mul_f32 v[48:49], v[46:47], v[48:49]
	v_pk_mul_f32 v[46:47], v[152:153], v[152:153]
	v_add_f32_e32 v58, v104, v105
	v_fma_f32 v154, v32, v114, 0
	v_add_f32_e32 v46, v58, v46
	v_fmac_f32_e32 v154, v33, v115
	v_pk_mul_f32 v[114:115], v[126:127], v[48:49]
	v_add_f32_e32 v46, v47, v46
	v_fmac_f32_e32 v154, v34, v114
	v_fmac_f32_e32 v154, v35, v115
	v_add_f32_dpp v46, v46, v46 quad_perm:[1,0,3,2] row_mask:0xf bank_mask:0xf bound_ctrl:1
	s_nop 1
	v_add_f32_dpp v46, v46, v46 quad_perm:[2,3,0,1] row_mask:0xf bank_mask:0xf bound_ctrl:1
	s_nop 1
	v_add_f32_dpp v58, v46, v46 row_half_mirror row_mask:0xf bank_mask:0xf bound_ctrl:1
	v_add_f32_dpp v46, v154, v154 quad_perm:[1,0,3,2] row_mask:0xf bank_mask:0xf bound_ctrl:1
	s_nop 0
	v_mov_b32_dpp v103, v58 row_mirror row_mask:0xf bank_mask:0xf bound_ctrl:1
	v_add_f32_dpp v46, v46, v46 quad_perm:[2,3,0,1] row_mask:0xf bank_mask:0xf bound_ctrl:1
	s_nop 1
	v_add_f32_dpp v46, v46, v46 row_half_mirror row_mask:0xf bank_mask:0xf bound_ctrl:1
	s_nop 1
	v_mov_b32_dpp v47, v46 row_mirror row_mask:0xf bank_mask:0xf bound_ctrl:1
	s_and_saveexec_b64 s[10:11], s[6:7]
	s_cbranch_execz .LBB0_205
	v_lshlrev_b64 v[104:105], 6, v[122:123]
	v_lshl_add_u64 v[104:105], v[98:99], 0, v[104:105]
	v_add_f32_e32 v46, v46, v47
	global_store_dword v[104:105], v46, off nt
.LBB0_205:
	s_or_b64 exec, exec, s[10:11]
	v_lshlrev_b32_e32 v46, 16, v36
	v_add_f32_e32 v46, v8, v46
	v_mul_f32_e32 v46, 0xbfb8aa3b, v46
	v_exp_f32_e32 v123, v46
	v_lshlrev_b32_e32 v114, 16, v120
	v_and_b32_e32 v115, 0xffff0000, v120
	v_pk_add_f32 v[112:113], v[112:113], v[114:115] neg_lo:[0,1] neg_hi:[0,1]
	v_add_f32_e32 v120, 1.0, v123
	v_rcp_f32_e32 v120, v120
	v_lshlrev_b32_e32 v46, 16, v121
	v_and_b32_e32 v47, 0xffff0000, v121
	v_and_b32_e32 v121, 0xffff0000, v36
	v_pk_fma_f32 v[112:113], v[4:5], v[112:113], v[114:115]
	v_lshlrev_b32_e32 v123, 16, v37
	v_and_b32_e32 v155, 0xffff0000, v37
	v_mul_f32_e32 v36, 0xbf1b4598, v120
	v_mul_f32_e32 v37, 0xbfb8aa3b, v112
	v_add_f32_e32 v120, v9, v121
	v_exp_f32_e32 v37, v37
	v_mul_f32_e32 v120, 0xbfb8aa3b, v120
	v_exp_f32_e32 v121, v120
	v_add_f32_e32 v123, v10, v123
	v_add_f32_e32 v37, 1.0, v37
	v_rcp_f32_e32 v120, v37
	v_add_f32_e32 v37, 1.0, v121
	v_mul_f32_e32 v121, 0xbfb8aa3b, v113
	v_mul_f32_e32 v123, 0xbfb8aa3b, v123
	v_exp_f32_e32 v121, v121
	v_exp_f32_e32 v123, v123
	v_rcp_f32_e32 v37, v37
	v_pk_add_f32 v[50:51], v[50:51], v[46:47] neg_lo:[0,1] neg_hi:[0,1]
	v_add_f32_e32 v121, 1.0, v121
	v_add_f32_e32 v123, 1.0, v123
	v_rcp_f32_e32 v121, v121
	v_rcp_f32_e32 v123, v123
	v_pk_fma_f32 v[50:51], v[6:7], v[50:51], v[46:47]
	v_mul_f32_e32 v37, 0xbf1b4598, v37
	v_pk_mul_f32 v[112:113], v[112:113], v[120:121]
	v_mul_f32_e32 v120, 0xbf1b4598, v123
	v_add_f32_e32 v121, v11, v155
	v_mul_f32_e32 v120, 0x3fb8aa3b, v120
	v_mul_f32_e32 v121, 0xbfb8aa3b, v121
	v_exp_f32_e32 v154, v120
	v_mul_f32_e32 v120, 0xbfb8aa3b, v50
	v_exp_f32_e32 v121, v121
	v_mul_f32_e32 v123, 0xbfb8aa3b, v51
	v_exp_f32_e32 v120, v120
	v_exp_f32_e32 v123, v123
	v_mul_f32_e32 v36, 0x3fb8aa3b, v36
	v_mul_f32_e32 v37, 0x3fb8aa3b, v37
	v_exp_f32_e32 v36, v36
	v_exp_f32_e32 v37, v37
	v_add_f32_e32 v121, 1.0, v121
	v_add_f32_e32 v120, 1.0, v120
	v_rcp_f32_e32 v155, v121
	v_add_f32_e32 v121, 1.0, v123
	v_rcp_f32_e32 v120, v120
	v_rcp_f32_e32 v121, v121
	v_add_f32_e32 v58, v58, v103
	v_max_f32_e32 v58, 0x179abe15, v58
	v_pk_add_f32 v[36:37], v[36:37], -1.0 op_sel_hi:[1,0]
	v_mul_f32_e32 v123, 0xbf1b4598, v155
	v_rsq_f32_e32 v58, v58
	v_pk_add_f32 v[36:37], v[36:37], 1.0 op_sel_hi:[1,0]
	v_mul_f32_e32 v123, 0x3fb8aa3b, v123
	v_pk_mul_f32 v[50:51], v[50:51], v[120:121]
	v_pk_mul_f32 v[120:121], v[116:117], v[36:37]
	v_exp_f32_e32 v155, v123
	v_rcp_f32_e32 v36, v120
	v_rcp_f32_e32 v37, v121
	v_pk_mul_f32 v[150:151], v[150:151], v[58:59] op_sel_hi:[1,0]
	v_lshlrev_b32_e32 v104, 16, v40
	v_pk_mul_f32 v[178:179], v[116:117], v[150:151]
	v_pk_mul_f32 v[116:117], v[124:125], v[150:151]
	v_pk_mul_f32 v[150:151], v[152:153], v[58:59] op_sel_hi:[1,0]
	v_pk_mul_f32 v[124:125], v[116:117], v[36:37]
	v_pk_mul_f32 v[36:37], v[106:107], v[36:37]
	v_pk_add_f32 v[106:107], v[154:155], -1.0 op_sel_hi:[1,0]
	v_pk_mul_f32 v[148:149], v[148:149], v[150:151]
	v_pk_add_f32 v[106:107], v[106:107], 1.0 op_sel_hi:[1,0]
	v_and_b32_e32 v105, 0xffff0000, v40
	v_pk_mul_f32 v[116:117], v[118:119], v[106:107]
	v_lshlrev_b32_e32 v40, 16, v41
	v_rcp_f32_e32 v106, v116
	v_rcp_f32_e32 v107, v117
	v_and_b32_e32 v41, 0xffff0000, v41
	v_pk_mul_f32 v[38:39], v[38:39], v[120:121]
	v_pk_mul_f32 v[126:127], v[126:127], v[116:117]
	v_pk_mul_f32 v[148:149], v[148:149], v[106:107]
	v_pk_mul_f32 v[48:49], v[48:49], v[106:107]
	v_mad_i64_i32 v[106:107], s[10:11], v122, s23, v[56:57]
	v_lshlrev_b64 v[106:107], 1, v[106:107]
	v_pk_add_f32 v[54:55], v[54:55], v[104:105] neg_lo:[0,1] neg_hi:[0,1]
	v_pk_add_f32 v[42:43], v[42:43], v[40:41] neg_lo:[0,1] neg_hi:[0,1]
	v_cvt_pk_bf16_f32 v38, v38, v39
	v_cvt_pk_bf16_f32 v39, v126, v127
	v_lshl_add_u64 v[122:123], s[74:75], 0, v[106:107]
	v_pk_fma_f32 v[54:55], v[0:1], v[54:55], v[104:105]
	v_pk_fma_f32 v[42:43], v[2:3], v[42:43], v[40:41]
	global_store_dwordx2 v[122:123], v[38:39], off nt
	v_cvt_pk_bf16_f32 v36, v36, v37
	v_cvt_pk_bf16_f32 v37, v48, v49
	v_lshl_add_u64 v[38:39], s[76:77], 0, v[106:107]
	v_pk_mul_f32 v[118:119], v[118:119], v[150:151]
	global_store_dwordx2 v[38:39], v[36:37], off nt
	v_cvt_pk_bf16_f32 v36, v54, v55
	v_cvt_pk_bf16_f32 v37, v42, v43
	v_lshl_add_u64 v[38:39], s[78:79], 0, v[106:107]
	global_store_dwordx2 v[38:39], v[36:37], off nt
	v_cvt_pk_bf16_f32 v36, v178, v179
	v_cvt_pk_bf16_f32 v37, v118, v119
	v_lshl_add_u64 v[38:39], s[80:81], 0, v[106:107]
	global_store_dwordx2 v[38:39], v[36:37], off nt
	v_cvt_pk_bf16_f32 v36, v124, v125
	v_cvt_pk_bf16_f32 v37, v148, v149
	v_lshl_add_u64 v[38:39], s[82:83], 0, v[106:107]
	global_store_dwordx2 v[38:39], v[36:37], off nt
	v_cvt_pk_bf16_f32 v36, v112, v113
	v_cvt_pk_bf16_f32 v37, v50, v51
	v_lshl_add_u64 v[38:39], s[84:85], 0, v[106:107]
	v_add_u32_e32 v122, 5, v102
	global_store_dwordx2 v[38:39], v[36:37], off nt
	v_mad_i64_i32 v[36:37], s[10:11], v122, s22, v[60:61]
	v_add_co_u32_e32 v36, vcc, s2, v36
	v_ashrrev_i32_e32 v123, 31, v122
	s_nop 0
	v_addc_co_u32_e32 v37, vcc, 0, v37, vcc
	s_waitcnt vmcnt(16)
	v_mov_b64_e32 v[48:49], v[246:247]
	v_mov_b64_e32 v[50:51], v[248:249]
	v_mov_b64_e32 v[42:43], v[250:251]
	v_mov_b64_e32 v[118:119], v[254:255]
	v_add_u32_e32 v242, 7, v102
	v_mad_i64_i32 v[242:243], s[26:27], v242, s22, v[60:61]
	global_load_dwordx2 v[246:247], v[242:243], off
	global_load_dwordx2 v[248:249], v[242:243], off offset:2048
	v_add_co_u32_e32 v244, vcc, s2, v242
	s_nop 1
	v_addc_co_u32_e32 v245, vcc, 0, v243, vcc
	global_load_dwordx2 v[250:251], v[244:245], off
	global_load_dwordx2 v[254:255], v[244:245], off offset:2048
	ds_read2st64_b64 v[36:39], v171 offset0:16 offset1:80
	s_waitcnt lgkmcnt(0)
	v_lshlrev_b32_e32 v54, 16, v38
	v_and_b32_e32 v38, 0xffff0000, v38
	v_lshlrev_b32_e32 v58, 16, v39
	v_and_b32_e32 v103, 0xffff0000, v39
	v_add_f32_e32 v39, v12, v54
	v_add_f32_e32 v38, v13, v38
	v_mul_f32_e32 v39, 0xbfb8aa3b, v39
	v_mul_f32_e32 v38, 0xbfb8aa3b, v38
	v_exp_f32_e32 v39, v39
	v_exp_f32_e32 v54, v38
	v_add_f32_e32 v58, v14, v58
	v_mul_f32_e32 v58, 0xbfb8aa3b, v58
	v_add_f32_e32 v103, v15, v103
	v_add_f32_e32 v38, 1.0, v39
	v_add_f32_e32 v54, 1.0, v54
	v_exp_f32_e32 v58, v58
	v_mul_f32_e32 v103, 0xbfb8aa3b, v103
	v_rcp_f32_e32 v124, v38
	v_rcp_f32_e32 v125, v54
	v_exp_f32_e32 v103, v103
	v_add_f32_e32 v58, 1.0, v58
	v_rcp_f32_e32 v126, v58
	v_add_f32_e32 v58, 1.0, v103
	v_rcp_f32_e32 v127, v58
	v_lshlrev_b32_e32 v106, 16, v48
	v_and_b32_e32 v107, 0xffff0000, v48
	v_lshlrev_b32_e32 v112, 16, v50
	v_and_b32_e32 v113, 0xffff0000, v50
	v_pk_add_f32 v[38:39], v[108:109], v[106:107] neg_lo:[0,1] neg_hi:[0,1]
	v_pk_add_f32 v[54:55], v[110:111], v[112:113] neg_lo:[0,1] neg_hi:[0,1]
	v_pk_add_f32 v[108:109], v[124:125], -1.0 op_sel_hi:[1,0]
	v_pk_fma_f32 v[54:55], v[20:21], v[54:55], v[112:113]
	v_pk_fma_f32 v[108:109], v[28:29], v[108:109], 1.0 op_sel_hi:[1,1,0]
	v_pk_fma_f32 v[38:39], v[16:17], v[38:39], v[106:107]
	v_pk_mul_f32 v[108:109], v[54:55], v[108:109]
	v_lshlrev_b32_e32 v50, 16, v51
	v_and_b32_e32 v51, 0xffff0000, v51
	v_pk_mul_f32 v[110:111], v[38:39], v[108:109]
	v_pk_add_f32 v[52:53], v[52:53], v[50:51] neg_lo:[0,1] neg_hi:[0,1]
	v_fma_f32 v154, v32, v110, 0
	v_pk_mul_f32 v[148:149], v[24:25], v[54:55]
	v_fmac_f32_e32 v154, v33, v111
	v_pk_fma_f32 v[52:53], v[22:23], v[52:53], v[50:51]
	v_pk_add_f32 v[110:111], v[126:127], -1.0 op_sel_hi:[1,0]
	v_lshlrev_b32_e32 v48, 16, v49
	v_and_b32_e32 v49, 0xffff0000, v49
	v_pk_mul_f32 v[54:55], v[148:149], v[148:149]
	v_pk_fma_f32 v[110:111], v[30:31], v[110:111], 1.0 op_sel_hi:[1,1,0]
	v_pk_mul_f32 v[152:153], v[26:27], v[52:53]
	v_pk_add_f32 v[44:45], v[44:45], v[48:49] neg_lo:[0,1] neg_hi:[0,1]
	v_pk_mul_f32 v[150:151], v[52:53], v[110:111]
	v_pk_mul_f32 v[52:53], v[152:153], v[152:153]
	v_add_f32_e32 v54, v54, v55
	v_pk_fma_f32 v[44:45], v[18:19], v[44:45], v[48:49]
	v_add_f32_e32 v52, v54, v52
	v_pk_mul_f32 v[110:111], v[44:45], v[150:151]
	v_add_f32_e32 v52, v53, v52
	v_fmac_f32_e32 v154, v34, v110
	v_fmac_f32_e32 v154, v35, v111
	v_add_f32_dpp v52, v52, v52 quad_perm:[1,0,3,2] row_mask:0xf bank_mask:0xf bound_ctrl:1
	s_nop 1
	v_add_f32_dpp v52, v52, v52 quad_perm:[2,3,0,1] row_mask:0xf bank_mask:0xf bound_ctrl:1
	s_nop 1
	v_add_f32_dpp v58, v52, v52 row_half_mirror row_mask:0xf bank_mask:0xf bound_ctrl:1
	v_add_f32_dpp v52, v154, v154 quad_perm:[1,0,3,2] row_mask:0xf bank_mask:0xf bound_ctrl:1
	s_nop 0
	v_mov_b32_dpp v103, v58 row_mirror row_mask:0xf bank_mask:0xf bound_ctrl:1
	v_add_f32_dpp v52, v52, v52 quad_perm:[2,3,0,1] row_mask:0xf bank_mask:0xf bound_ctrl:1
	s_nop 1
	v_add_f32_dpp v52, v52, v52 row_half_mirror row_mask:0xf bank_mask:0xf bound_ctrl:1
	s_nop 1
	v_mov_b32_dpp v53, v52 row_mirror row_mask:0xf bank_mask:0xf bound_ctrl:1
	s_and_saveexec_b64 s[10:11], s[6:7]
	s_cbranch_execz .LBB0_207
	v_lshlrev_b64 v[54:55], 6, v[122:123]
	v_lshl_add_u64 v[54:55], v[98:99], 0, v[54:55]
	v_add_f32_e32 v52, v52, v53
	global_store_dword v[54:55], v52, off nt
.LBB0_207:
	s_or_b64 exec, exec, s[10:11]
	v_lshlrev_b32_e32 v52, 16, v36
	v_add_f32_e32 v52, v8, v52
	v_mul_f32_e32 v52, 0xbfb8aa3b, v52
	v_exp_f32_e32 v123, v52
	v_lshlrev_b32_e32 v110, 16, v118
	v_and_b32_e32 v111, 0xffff0000, v118
	v_pk_add_f32 v[114:115], v[114:115], v[110:111] neg_lo:[0,1] neg_hi:[0,1]
	v_add_f32_e32 v118, 1.0, v123
	v_rcp_f32_e32 v118, v118
	v_lshlrev_b32_e32 v52, 16, v119
	v_and_b32_e32 v53, 0xffff0000, v119
	v_and_b32_e32 v119, 0xffff0000, v36
	v_pk_fma_f32 v[114:115], v[4:5], v[114:115], v[110:111]
	v_lshlrev_b32_e32 v123, 16, v37
	v_and_b32_e32 v155, 0xffff0000, v37
	v_mul_f32_e32 v36, 0xbf1b4598, v118
	v_mul_f32_e32 v37, 0xbfb8aa3b, v114
	v_add_f32_e32 v118, v9, v119
	v_exp_f32_e32 v37, v37
	v_mul_f32_e32 v118, 0xbfb8aa3b, v118
	v_exp_f32_e32 v119, v118
	v_add_f32_e32 v123, v10, v123
	v_add_f32_e32 v37, 1.0, v37
	v_rcp_f32_e32 v118, v37
	v_add_f32_e32 v37, 1.0, v119
	v_mul_f32_e32 v119, 0xbfb8aa3b, v115
	v_mul_f32_e32 v123, 0xbfb8aa3b, v123
	v_exp_f32_e32 v119, v119
	v_exp_f32_e32 v123, v123
	v_rcp_f32_e32 v37, v37
	v_pk_add_f32 v[46:47], v[46:47], v[52:53] neg_lo:[0,1] neg_hi:[0,1]
	v_add_f32_e32 v119, 1.0, v119
	v_add_f32_e32 v123, 1.0, v123
	v_rcp_f32_e32 v119, v119
	v_rcp_f32_e32 v123, v123
	v_pk_fma_f32 v[46:47], v[6:7], v[46:47], v[52:53]
	v_mul_f32_e32 v37, 0xbf1b4598, v37
	v_pk_mul_f32 v[114:115], v[114:115], v[118:119]
	v_mul_f32_e32 v118, 0xbf1b4598, v123
	v_add_f32_e32 v119, v11, v155
	v_mul_f32_e32 v118, 0x3fb8aa3b, v118
	v_mul_f32_e32 v119, 0xbfb8aa3b, v119
	v_exp_f32_e32 v154, v118
	v_mul_f32_e32 v118, 0xbfb8aa3b, v46
	v_exp_f32_e32 v119, v119
	v_mul_f32_e32 v123, 0xbfb8aa3b, v47
	v_exp_f32_e32 v118, v118
	v_exp_f32_e32 v123, v123
	v_mul_f32_e32 v36, 0x3fb8aa3b, v36
	v_mul_f32_e32 v37, 0x3fb8aa3b, v37
	v_exp_f32_e32 v36, v36
	v_exp_f32_e32 v37, v37
	v_add_f32_e32 v119, 1.0, v119
	v_add_f32_e32 v118, 1.0, v118
	v_rcp_f32_e32 v155, v119
	v_add_f32_e32 v119, 1.0, v123
	v_rcp_f32_e32 v118, v118
	v_rcp_f32_e32 v119, v119
	v_add_f32_e32 v58, v58, v103
	v_max_f32_e32 v58, 0x179abe15, v58
	v_pk_add_f32 v[36:37], v[36:37], -1.0 op_sel_hi:[1,0]
	v_mul_f32_e32 v123, 0xbf1b4598, v155
	v_rsq_f32_e32 v58, v58
	v_pk_add_f32 v[36:37], v[36:37], 1.0 op_sel_hi:[1,0]
	v_mul_f32_e32 v123, 0x3fb8aa3b, v123
	v_pk_mul_f32 v[46:47], v[46:47], v[118:119]
	v_pk_mul_f32 v[118:119], v[120:121], v[36:37]
	v_exp_f32_e32 v155, v123
	v_rcp_f32_e32 v36, v118
	v_rcp_f32_e32 v37, v119
	v_pk_mul_f32 v[148:149], v[148:149], v[58:59] op_sel_hi:[1,0]
	v_pk_mul_f32 v[38:39], v[38:39], v[118:119]
	v_pk_mul_f32 v[178:179], v[120:121], v[148:149]
	v_pk_mul_f32 v[120:121], v[124:125], v[148:149]
	v_pk_mul_f32 v[148:149], v[152:153], v[58:59] op_sel_hi:[1,0]
	v_pk_mul_f32 v[124:125], v[120:121], v[36:37]
	v_pk_mul_f32 v[36:37], v[108:109], v[36:37]
	v_pk_add_f32 v[108:109], v[154:155], -1.0 op_sel_hi:[1,0]
	v_mad_i64_i32 v[122:123], s[10:11], v122, s23, v[56:57]
	v_pk_add_f32 v[108:109], v[108:109], 1.0 op_sel_hi:[1,0]
	v_lshlrev_b32_e32 v54, 16, v42
	v_pk_mul_f32 v[120:121], v[116:117], v[108:109]
	v_and_b32_e32 v55, 0xffff0000, v42
	v_rcp_f32_e32 v108, v120
	v_rcp_f32_e32 v109, v121
	v_pk_mul_f32 v[44:45], v[44:45], v[120:121]
	v_lshlrev_b32_e32 v42, 16, v43
	v_and_b32_e32 v43, 0xffff0000, v43
	v_pk_mul_f32 v[126:127], v[126:127], v[148:149]
	v_cvt_pk_bf16_f32 v38, v38, v39
	v_cvt_pk_bf16_f32 v39, v44, v45
	v_lshlrev_b64 v[44:45], 1, v[122:123]
	v_pk_add_f32 v[104:105], v[104:105], v[54:55] neg_lo:[0,1] neg_hi:[0,1]
	v_pk_add_f32 v[40:41], v[40:41], v[42:43] neg_lo:[0,1] neg_hi:[0,1]
	v_pk_mul_f32 v[126:127], v[126:127], v[108:109]
	v_pk_mul_f32 v[108:109], v[150:151], v[108:109]
	v_lshl_add_u64 v[122:123], s[74:75], 0, v[44:45]
	v_pk_fma_f32 v[104:105], v[0:1], v[104:105], v[54:55]
	v_pk_fma_f32 v[40:41], v[2:3], v[40:41], v[42:43]
	global_store_dwordx2 v[122:123], v[38:39], off nt
	v_cvt_pk_bf16_f32 v36, v36, v37
	v_cvt_pk_bf16_f32 v37, v108, v109
	v_lshl_add_u64 v[38:39], s[76:77], 0, v[44:45]
	v_pk_mul_f32 v[116:117], v[116:117], v[148:149]
	global_store_dwordx2 v[38:39], v[36:37], off nt
	v_cvt_pk_bf16_f32 v36, v104, v105
	v_cvt_pk_bf16_f32 v37, v40, v41
	v_lshl_add_u64 v[38:39], s[78:79], 0, v[44:45]
	global_store_dwordx2 v[38:39], v[36:37], off nt
	v_cvt_pk_bf16_f32 v36, v178, v179
	v_cvt_pk_bf16_f32 v37, v116, v117
	v_lshl_add_u64 v[38:39], s[80:81], 0, v[44:45]
	global_store_dwordx2 v[38:39], v[36:37], off nt
	v_cvt_pk_bf16_f32 v36, v124, v125
	v_cvt_pk_bf16_f32 v37, v126, v127
	v_lshl_add_u64 v[38:39], s[82:83], 0, v[44:45]
	global_store_dwordx2 v[38:39], v[36:37], off nt
	v_cvt_pk_bf16_f32 v36, v114, v115
	v_cvt_pk_bf16_f32 v37, v46, v47
	v_lshl_add_u64 v[38:39], s[84:85], 0, v[44:45]
	v_add_u32_e32 v116, 6, v102
	global_store_dwordx2 v[38:39], v[36:37], off nt
	v_mad_i64_i32 v[36:37], s[10:11], v116, s22, v[60:61]
	v_add_co_u32_e32 v36, vcc, s2, v36
	v_ashrrev_i32_e32 v117, 31, v116
	s_nop 0
	v_addc_co_u32_e32 v37, vcc, 0, v37, vcc
	s_waitcnt vmcnt(16)
	v_mov_b64_e32 v[44:45], v[234:235]
	v_mov_b64_e32 v[46:47], v[236:237]
	v_mov_b64_e32 v[40:41], v[238:239]
	v_mov_b64_e32 v[152:153], v[240:241]
	ds_read2st64_b64 v[36:39], v172 offset0:16 offset1:80
	s_waitcnt lgkmcnt(0)
	v_lshlrev_b32_e32 v58, 16, v38
	v_and_b32_e32 v38, 0xffff0000, v38
	v_add_f32_e32 v38, v13, v38
	v_mul_f32_e32 v38, 0xbfb8aa3b, v38
	v_lshlrev_b32_e32 v103, 16, v39
	v_and_b32_e32 v124, 0xffff0000, v39
	v_add_f32_e32 v39, v12, v58
	v_exp_f32_e32 v58, v38
	v_mul_f32_e32 v39, 0xbfb8aa3b, v39
	v_exp_f32_e32 v39, v39
	v_add_f32_e32 v58, 1.0, v58
	v_rcp_f32_e32 v123, v58
	v_add_f32_e32 v58, v14, v103
	v_mul_f32_e32 v58, 0xbfb8aa3b, v58
	v_add_f32_e32 v103, v15, v124
	v_add_f32_e32 v38, 1.0, v39
	v_exp_f32_e32 v58, v58
	v_mul_f32_e32 v103, 0xbfb8aa3b, v103
	v_rcp_f32_e32 v122, v38
	v_exp_f32_e32 v103, v103
	v_add_f32_e32 v58, 1.0, v58
	v_rcp_f32_e32 v124, v58
	v_add_f32_e32 v58, 1.0, v103
	v_rcp_f32_e32 v125, v58
	v_lshlrev_b32_e32 v108, 16, v44
	v_and_b32_e32 v109, 0xffff0000, v44
	v_lshlrev_b32_e32 v114, 16, v46
	v_and_b32_e32 v115, 0xffff0000, v46
	v_pk_add_f32 v[38:39], v[106:107], v[108:109] neg_lo:[0,1] neg_hi:[0,1]
	v_pk_add_f32 v[104:105], v[112:113], v[114:115] neg_lo:[0,1] neg_hi:[0,1]
	v_pk_add_f32 v[106:107], v[122:123], -1.0 op_sel_hi:[1,0]
	v_pk_fma_f32 v[104:105], v[20:21], v[104:105], v[114:115]
	v_pk_fma_f32 v[106:107], v[28:29], v[106:107], 1.0 op_sel_hi:[1,1,0]
	v_pk_fma_f32 v[38:39], v[16:17], v[38:39], v[108:109]
	v_pk_mul_f32 v[106:107], v[104:105], v[106:107]
	v_lshlrev_b32_e32 v44, 16, v45
	v_and_b32_e32 v45, 0xffff0000, v45
	v_pk_mul_f32 v[112:113], v[38:39], v[106:107]
	v_lshlrev_b32_e32 v46, 16, v47
	v_and_b32_e32 v47, 0xffff0000, v47
	v_fma_f32 v154, v32, v112, 0
	v_pk_add_f32 v[48:49], v[48:49], v[44:45] neg_lo:[0,1] neg_hi:[0,1]
	v_fmac_f32_e32 v154, v33, v113
	v_pk_fma_f32 v[112:113], v[18:19], v[48:49], v[44:45]
	v_pk_add_f32 v[48:49], v[50:51], v[46:47] neg_lo:[0,1] neg_hi:[0,1]
	v_pk_add_f32 v[50:51], v[124:125], -1.0 op_sel_hi:[1,0]
	v_pk_fma_f32 v[48:49], v[22:23], v[48:49], v[46:47]
	v_pk_fma_f32 v[50:51], v[30:31], v[50:51], 1.0 op_sel_hi:[1,1,0]
	v_pk_mul_f32 v[126:127], v[24:25], v[104:105]
	v_pk_mul_f32 v[148:149], v[48:49], v[50:51]
	v_pk_mul_f32 v[104:105], v[126:127], v[126:127]
	v_pk_mul_f32 v[50:51], v[112:113], v[148:149]
	v_pk_mul_f32 v[150:151], v[26:27], v[48:49]
	v_fmac_f32_e32 v154, v34, v50
	v_pk_mul_f32 v[48:49], v[150:151], v[150:151]
	v_add_f32_e32 v50, v104, v105
	v_add_f32_e32 v48, v50, v48
	v_add_f32_e32 v48, v49, v48
	v_fmac_f32_e32 v154, v35, v51
	s_nop 0
	v_add_f32_dpp v48, v48, v48 quad_perm:[1,0,3,2] row_mask:0xf bank_mask:0xf bound_ctrl:1
	s_nop 1
	v_add_f32_dpp v48, v48, v48 quad_perm:[2,3,0,1] row_mask:0xf bank_mask:0xf bound_ctrl:1
	s_nop 1
	v_add_f32_dpp v58, v48, v48 row_half_mirror row_mask:0xf bank_mask:0xf bound_ctrl:1
	v_add_f32_dpp v48, v154, v154 quad_perm:[1,0,3,2] row_mask:0xf bank_mask:0xf bound_ctrl:1
	s_nop 0
	v_mov_b32_dpp v103, v58 row_mirror row_mask:0xf bank_mask:0xf bound_ctrl:1
	v_add_f32_dpp v48, v48, v48 quad_perm:[2,3,0,1] row_mask:0xf bank_mask:0xf bound_ctrl:1
	s_nop 1
	v_add_f32_dpp v48, v48, v48 row_half_mirror row_mask:0xf bank_mask:0xf bound_ctrl:1
	s_nop 1
	v_mov_b32_dpp v49, v48 row_mirror row_mask:0xf bank_mask:0xf bound_ctrl:1
	s_and_saveexec_b64 s[10:11], s[6:7]
	s_cbranch_execz .LBB0_209
	v_lshlrev_b64 v[50:51], 6, v[116:117]
	v_lshl_add_u64 v[50:51], v[98:99], 0, v[50:51]
	v_add_f32_e32 v48, v48, v49
	global_store_dword v[50:51], v48, off nt
.LBB0_209:
	s_or_b64 exec, exec, s[10:11]
	v_lshlrev_b32_e32 v48, 16, v36
	v_add_f32_e32 v48, v8, v48
	v_mul_f32_e32 v48, 0xbfb8aa3b, v48
	v_exp_f32_e32 v117, v48
	v_lshlrev_b32_e32 v104, 16, v152
	v_and_b32_e32 v105, 0xffff0000, v152
	v_pk_add_f32 v[110:111], v[110:111], v[104:105] neg_lo:[0,1] neg_hi:[0,1]
	v_add_f32_e32 v117, 1.0, v117
	v_rcp_f32_e32 v117, v117
	v_and_b32_e32 v152, 0xffff0000, v36
	v_pk_fma_f32 v[110:111], v[4:5], v[110:111], v[104:105]
	v_lshlrev_b32_e32 v48, 16, v153
	v_and_b32_e32 v49, 0xffff0000, v153
	v_lshlrev_b32_e32 v153, 16, v37
	v_and_b32_e32 v178, 0xffff0000, v37
	v_mul_f32_e32 v36, 0xbf1b4598, v117
	v_mul_f32_e32 v37, 0xbfb8aa3b, v110
	v_add_f32_e32 v117, v9, v152
	v_exp_f32_e32 v37, v37
	v_mul_f32_e32 v117, 0xbfb8aa3b, v117
	v_exp_f32_e32 v117, v117
	v_add_f32_e32 v153, v10, v153
	v_add_f32_e32 v37, 1.0, v37
	v_rcp_f32_e32 v152, v37
	v_add_f32_e32 v37, 1.0, v117
	v_mul_f32_e32 v117, 0xbfb8aa3b, v111
	v_exp_f32_e32 v117, v117
	v_mul_f32_e32 v153, 0xbfb8aa3b, v153
	v_exp_f32_e32 v154, v153
	v_lshlrev_b32_e32 v50, 16, v40
	v_add_f32_e32 v117, 1.0, v117
	v_rcp_f32_e32 v153, v117
	v_add_f32_e32 v117, 1.0, v154
	v_rcp_f32_e32 v117, v117
	v_and_b32_e32 v51, 0xffff0000, v40
	v_lshlrev_b32_e32 v40, 16, v41
	v_and_b32_e32 v41, 0xffff0000, v41
	v_pk_add_f32 v[42:43], v[42:43], v[40:41] neg_lo:[0,1] neg_hi:[0,1]
	v_mul_f32_e32 v117, 0xbf1b4598, v117
	v_pk_fma_f32 v[154:155], v[2:3], v[42:43], v[40:41]
	v_pk_add_f32 v[42:43], v[52:53], v[48:49] neg_lo:[0,1] neg_hi:[0,1]
	v_add_f32_e32 v53, v11, v178
	v_mul_f32_e32 v117, 0x3fb8aa3b, v117
	v_pk_fma_f32 v[42:43], v[6:7], v[42:43], v[48:49]
	v_mul_f32_e32 v53, 0xbfb8aa3b, v53
	v_pk_mul_f32 v[110:111], v[110:111], v[152:153]
	v_exp_f32_e32 v152, v117
	v_mul_f32_e32 v52, 0xbfb8aa3b, v42
	v_exp_f32_e32 v53, v53
	v_mul_f32_e32 v117, 0xbfb8aa3b, v43
	v_rcp_f32_e32 v37, v37
	v_exp_f32_e32 v52, v52
	v_exp_f32_e32 v117, v117
	v_add_f32_e32 v53, 1.0, v53
	v_mul_f32_e32 v37, 0xbf1b4598, v37
	v_add_f32_e32 v52, 1.0, v52
	v_rcp_f32_e32 v153, v53
	v_add_f32_e32 v53, 1.0, v117
	v_mul_f32_e32 v36, 0x3fb8aa3b, v36
	v_mul_f32_e32 v37, 0x3fb8aa3b, v37
	v_rcp_f32_e32 v52, v52
	v_rcp_f32_e32 v53, v53
	v_exp_f32_e32 v36, v36
	v_exp_f32_e32 v37, v37
	v_mul_f32_e32 v117, 0xbf1b4598, v153
	v_pk_mul_f32 v[178:179], v[42:43], v[52:53]
	v_add_f32_e32 v42, v58, v103
	v_max_f32_e32 v42, 0x179abe15, v42
	v_pk_add_f32 v[36:37], v[36:37], -1.0 op_sel_hi:[1,0]
	v_rsq_f32_e32 v58, v42
	v_pk_add_f32 v[36:37], v[36:37], 1.0 op_sel_hi:[1,0]
	v_mul_f32_e32 v117, 0x3fb8aa3b, v117
	v_pk_mul_f32 v[42:43], v[118:119], v[36:37]
	v_exp_f32_e32 v153, v117
	v_rcp_f32_e32 v36, v42
	v_rcp_f32_e32 v37, v43
	v_pk_mul_f32 v[52:53], v[126:127], v[58:59] op_sel_hi:[1,0]
	v_pk_mul_f32 v[38:39], v[38:39], v[42:43]
	v_pk_mul_f32 v[118:119], v[118:119], v[52:53]
	v_pk_mul_f32 v[52:53], v[122:123], v[52:53]
	v_pk_mul_f32 v[126:127], v[150:151], v[58:59] op_sel_hi:[1,0]
	v_pk_mul_f32 v[122:123], v[52:53], v[36:37]
	v_pk_add_f32 v[52:53], v[152:153], -1.0 op_sel_hi:[1,0]
	v_pk_mul_f32 v[36:37], v[106:107], v[36:37]
	v_pk_add_f32 v[52:53], v[52:53], 1.0 op_sel_hi:[1,0]
	v_mad_i64_i32 v[116:117], s[10:11], v116, s23, v[56:57]
	v_pk_mul_f32 v[52:53], v[120:121], v[52:53]
	v_pk_mul_f32 v[124:125], v[124:125], v[126:127]
	v_rcp_f32_e32 v106, v52
	v_rcp_f32_e32 v107, v53
	v_pk_mul_f32 v[112:113], v[112:113], v[52:53]
	v_cvt_pk_bf16_f32 v38, v38, v39
	v_cvt_pk_bf16_f32 v39, v112, v113
	v_lshlrev_b64 v[112:113], 1, v[116:117]
	v_pk_add_f32 v[54:55], v[54:55], v[50:51] neg_lo:[0,1] neg_hi:[0,1]
	v_pk_mul_f32 v[124:125], v[124:125], v[106:107]
	v_pk_mul_f32 v[106:107], v[148:149], v[106:107]
	v_lshl_add_u64 v[116:117], s[74:75], 0, v[112:113]
	v_pk_fma_f32 v[54:55], v[0:1], v[54:55], v[50:51]
	global_store_dwordx2 v[116:117], v[38:39], off nt
	v_cvt_pk_bf16_f32 v36, v36, v37
	v_cvt_pk_bf16_f32 v37, v106, v107
	v_lshl_add_u64 v[38:39], s[76:77], 0, v[112:113]
	v_pk_mul_f32 v[120:121], v[120:121], v[126:127]
	global_store_dwordx2 v[38:39], v[36:37], off nt
	v_cvt_pk_bf16_f32 v36, v54, v55
	v_cvt_pk_bf16_f32 v37, v154, v155
	v_lshl_add_u64 v[38:39], s[78:79], 0, v[112:113]
	global_store_dwordx2 v[38:39], v[36:37], off nt
	v_cvt_pk_bf16_f32 v36, v118, v119
	v_cvt_pk_bf16_f32 v37, v120, v121
	v_lshl_add_u64 v[38:39], s[80:81], 0, v[112:113]
	global_store_dwordx2 v[38:39], v[36:37], off nt
	v_cvt_pk_bf16_f32 v36, v122, v123
	v_cvt_pk_bf16_f32 v37, v124, v125
	v_lshl_add_u64 v[38:39], s[82:83], 0, v[112:113]
	global_store_dwordx2 v[38:39], v[36:37], off nt
	v_cvt_pk_bf16_f32 v36, v110, v111
	v_cvt_pk_bf16_f32 v37, v178, v179
	v_lshl_add_u64 v[38:39], s[84:85], 0, v[112:113]
	v_add_u32_e32 v54, s20, v173
	global_store_dwordx2 v[38:39], v[36:37], off nt
	v_mad_i64_i32 v[36:37], s[10:11], v54, s22, v[60:61]
	v_add_co_u32_e32 v36, vcc, s2, v36
	v_ashrrev_i32_e32 v55, 31, v54
	s_nop 0
	v_addc_co_u32_e32 v37, vcc, 0, v37, vcc
	s_waitcnt vmcnt(12)
	v_mov_b64_e32 v[106:107], v[246:247]
	v_mov_b64_e32 v[110:111], v[248:249]
	v_mov_b64_e32 v[118:119], v[250:251]
	v_mov_b64_e32 v[116:117], v[254:255]
	ds_read2st64_b64 v[36:39], v174 offset0:16 offset1:80
	s_waitcnt lgkmcnt(0)
	v_lshlrev_b32_e32 v58, 16, v38
	v_add_f32_e32 v58, v12, v58
	v_mul_f32_e32 v58, 0xbfb8aa3b, v58
	v_exp_f32_e32 v58, v58
	v_and_b32_e32 v38, 0xffff0000, v38
	v_add_f32_e32 v38, v13, v38
	v_mul_f32_e32 v38, 0xbfb8aa3b, v38
	v_lshlrev_b32_e32 v103, 16, v39
	v_and_b32_e32 v126, 0xffff0000, v39
	v_add_f32_e32 v39, 1.0, v58
	v_exp_f32_e32 v58, v38
	v_lshlrev_b32_e32 v112, 16, v106
	v_add_f32_e32 v58, 1.0, v58
	v_and_b32_e32 v113, 0xffff0000, v106
	v_lshlrev_b32_e32 v120, 16, v107
	v_and_b32_e32 v121, 0xffff0000, v107
	v_rcp_f32_e32 v106, v39
	v_rcp_f32_e32 v107, v58
	v_add_f32_e32 v58, v14, v103
	v_mul_f32_e32 v58, 0xbfb8aa3b, v58
	v_add_f32_e32 v103, v15, v126
	v_lshlrev_b32_e32 v122, 16, v110
	v_and_b32_e32 v123, 0xffff0000, v110
	v_exp_f32_e32 v58, v58
	v_mul_f32_e32 v103, 0xbfb8aa3b, v103
	v_lshlrev_b32_e32 v124, 16, v111
	v_and_b32_e32 v125, 0xffff0000, v111
	v_pk_add_f32 v[38:39], v[108:109], v[112:113] neg_lo:[0,1] neg_hi:[0,1]
	v_pk_add_f32 v[108:109], v[114:115], v[122:123] neg_lo:[0,1] neg_hi:[0,1]
	v_pk_add_f32 v[110:111], v[106:107], -1.0 op_sel_hi:[1,0]
	v_exp_f32_e32 v103, v103
	v_pk_fma_f32 v[108:109], v[20:21], v[108:109], v[122:123]
	v_pk_fma_f32 v[110:111], v[28:29], v[110:111], 1.0 op_sel_hi:[1,1,0]
	v_pk_fma_f32 v[38:39], v[16:17], v[38:39], v[112:113]
	v_pk_mul_f32 v[112:113], v[24:25], v[108:109]
	v_pk_mul_f32 v[108:109], v[108:109], v[110:111]
	v_add_f32_e32 v58, 1.0, v58
	v_pk_mul_f32 v[110:111], v[38:39], v[108:109]
	v_pk_add_f32 v[46:47], v[46:47], v[124:125] neg_lo:[0,1] neg_hi:[0,1]
	v_fma_f32 v127, v32, v110, 0
	v_rcp_f32_e32 v110, v58
	v_add_f32_e32 v58, 1.0, v103
	v_fmac_f32_e32 v127, v33, v111
	v_rcp_f32_e32 v111, v58
	v_pk_fma_f32 v[46:47], v[22:23], v[46:47], v[124:125]
	v_pk_mul_f32 v[122:123], v[112:113], v[112:113]
	v_pk_add_f32 v[44:45], v[44:45], v[120:121] neg_lo:[0,1] neg_hi:[0,1]
	v_pk_mul_f32 v[114:115], v[26:27], v[46:47]
	v_pk_fma_f32 v[44:45], v[18:19], v[44:45], v[120:121]
	v_pk_mul_f32 v[120:121], v[114:115], v[114:115]
	v_add_f32_e32 v58, v122, v123
	v_add_f32_e32 v58, v58, v120
	v_add_f32_e32 v58, v121, v58
	v_pk_add_f32 v[120:121], v[110:111], -1.0 op_sel_hi:[1,0]
	s_nop 0
	v_pk_fma_f32 v[120:121], v[30:31], v[120:121], 1.0 op_sel_hi:[1,1,0]
	v_add_f32_dpp v58, v58, v58 quad_perm:[1,0,3,2] row_mask:0xf bank_mask:0xf bound_ctrl:1
	v_pk_mul_f32 v[46:47], v[46:47], v[120:121]
	s_nop 0
	v_pk_mul_f32 v[120:121], v[44:45], v[46:47]
	v_add_f32_dpp v58, v58, v58 quad_perm:[2,3,0,1] row_mask:0xf bank_mask:0xf bound_ctrl:1
	v_fmac_f32_e32 v127, v34, v120
	v_fmac_f32_e32 v127, v35, v121
	v_add_f32_dpp v58, v58, v58 row_half_mirror row_mask:0xf bank_mask:0xf bound_ctrl:1
	s_nop 0
	v_add_f32_dpp v120, v127, v127 quad_perm:[1,0,3,2] row_mask:0xf bank_mask:0xf bound_ctrl:1
	v_mov_b32_dpp v103, v58 row_mirror row_mask:0xf bank_mask:0xf bound_ctrl:1
	s_nop 0
	v_add_f32_dpp v120, v120, v120 quad_perm:[2,3,0,1] row_mask:0xf bank_mask:0xf bound_ctrl:1
	s_nop 1
	v_add_f32_dpp v120, v120, v120 row_half_mirror row_mask:0xf bank_mask:0xf bound_ctrl:1
	s_nop 1
	v_mov_b32_dpp v121, v120 row_mirror row_mask:0xf bank_mask:0xf bound_ctrl:1
	s_and_saveexec_b64 s[10:11], s[6:7]
	s_cbranch_execz .LBB0_162
	v_lshlrev_b64 v[122:123], 6, v[54:55]
	v_lshl_add_u64 v[122:123], v[98:99], 0, v[122:123]
	v_add_f32_e32 v55, v120, v121
	global_store_dword v[122:123], v55, off nt
	s_branch .LBB0_162
